# k19 + filt_pipe: implicit-filter MFMA blocks software-pipelined (next block's first 7 w3 loads + decay load issued before the current block's tail, row addresses precomputed, vmcnt waits recomputed)
# speedup vs baseline: 1.0446x; 1.0054x over previous
; __device__ __forceinline__ void filt_item(const Params& p, int lsel, int tile, float* lds, int wave, float (&colsum)[16], bool flush) {
;     const int tid = fresh_tid(wave);
;     const int L = lsel ? TS : TP; const int t0 = tile * 16;
;     float* filt = (float*)(p.ws + (lsel ? WS_FILTS : WS_FILTP));
;     float* normsum = (float*)(p.ws + WS_NORM) + lsel * 2048;
;     float* feat = lds;
;     float* h1 = lds + 16 * 36;
;     float* h2 = h1 + 16 * 64;
;     __syncthreads();
;     if (tid < 16 * 17) { const int t = tid / 17, j = tid % 17; const int tt = t0 + t;
;         if (j == 16) feat[t * 36] = (float)tt / (float)(L - 1);
;         else { const float band = 1e-4f + (float)j * ((15.0f - 1e-4f) / 15.0f);
;             double turns = (double)tt * (double)band / (double)L; turns -= floor(turns);
;             float s, c; sincospif((float)(2.0 * turns), &s, &c);
;             feat[t * 36 + 1 + j] = c; feat[t * 36 + 17 + j] = s; } }
;     __syncthreads();
;     for (int e = tid; e < 1024; e += NTHR) { const int t = e >> 6, k = e & 63; float a = p.hy_pos_b1[k];
;         for (int f = 0; f < 33; ++f) a += feat[t * 36 + f] * p.hy_pos_w1[f * 64 + k];
;         h1[t * 64 + k] = sinf(p.hy_sin_freq[k] * a); }
;     __syncthreads();
;     for (int e = tid; e < 1024; e += NTHR) { const int t = e >> 6, k = e & 63; float a = p.hy_pos_b2[k];
;         for (int j = 0; j < 64; ++j) a += h1[t * 64 + j] * p.hy_pos_w2[j * 64 + k];
;         h2[t * 64 + k] = sinf(p.hy_sin_freq[64 + k] * a); }
;     __syncthreads();
;     {
;         const int lane = tid & 63, l15 = lane & 15, g = lane >> 4, wv = tid >> 6;
;         float av[16];
; #pragma unroll
;         for (int s_ = 0; s_ < 16; ++s_) av[s_] = h2[l15 * 64 + 4 * s_ + g];
;         const float inv_lm1 = 1.f / (float)(L - 1);
; #pragma unroll
;         for (int ct = 0; ct < 16; ++ct) {
;             const int col = wv * 256 + ct * 16 + l15;
;             const float* wp = p.hy_pos_w3 + (size_t)g * 2048 + col;
;             f32x4 acc = (f32x4){0.f, 0.f, 0.f, 0.f};
; #pragma unroll
;             for (int s_ = 0; s_ < 16; ++s_) acc = __builtin_amdgcn_mfma_f32_16x16x4f32(av[s_], wp[(size_t)s_ * 4 * 2048], acc, 0, 0, 0);
.LBB0_75:
	s_or_b64 exec, exec, s[8:9]
	s_and_b32 s0, 0xffff, s24
	s_cmp_lg_u32 s0, 0
	s_cselect_b64 s[0:1], -1, 0
	s_cmp_lg_u64 s[0:1], 0
	s_addc_u32 s4, s61, s93
	s_cmpk_gt_i32 s4, 0x47f
	s_cselect_b64 s[0:1], -1, 0
	s_cmpk_lt_i32 s4, 0x400
	s_cselect_b64 s[4:5], -1, 0
	s_xor_b64 s[4:5], s[30:31], s[4:5]
	s_or_b64 s[8:9], s[0:1], s[4:5]
	s_and_b64 s[0:1], s[30:31], exec
	s_mov_b32 s0, 0x29b00000
	v_readlane_b32 s4, v253, 8
	s_cselect_b32 s0, s0, 0x31b00000
	v_readlane_b32 s6, v253, 10
	v_readlane_b32 s5, v253, 9
	v_readlane_b32 s7, v253, 11
	s_add_u32 s4, s6, s0
	s_addc_u32 s5, s7, 0
	s_and_b64 s[0:1], s[30:31], exec
	s_cselect_b32 s0, 0x2000, 0
	s_add_u32 s6, s6, s0
	s_addc_u32 s7, s7, 0
	v_and_b32_e32 v10, 15, v14
	s_add_i32 s3, s3, -1
	s_movk_i32 s0, 0xff00
	v_and_or_b32 v2, v16, s0, v10
	s_and_b64 s[0:1], s[30:31], exec
	s_cselect_b32 s24, 14, 11
	s_ashr_i32 s29, s28, 31
	s_lshl_b64 s[0:1], s[28:29], 2
	v_bfe_u32 v30, v14, 4, 2
	s_add_u32 s0, s4, s0
	s_addc_u32 s1, s5, s1
	v_lshlrev_b32_e32 v0, 4, v30
	v_readlane_b32 s76, v253, 28
	v_lshl_add_u64 v[4:5], s[0:1], 0, v[0:1]
	v_lshlrev_b32_e32 v0, 13, v30
	v_readlane_b32 s90, v253, 42
	v_readlane_b32 s91, v253, 43
	v_ashrrev_i32_e32 v3, 31, v2
	v_lshlrev_b64 v[16:17], 2, v[2:3]
	v_lshl_add_u64 v[6:7], s[90:91], 0, v[0:1]
	v_lshl_add_u64 v[6:7], v[6:7], 0, v[16:17]
	s_mov_b32 s100, 0x8000
	s_mov_b32 s101, 0
	v_lshl_add_u64 v[204:205], v[6:7], 0, s[100:101]
	v_lshl_add_u64 v[206:207], v[204:205], 0, s[100:101]
	v_lshl_add_u64 v[208:209], v[206:207], 0, s[100:101]
	v_lshl_add_u64 v[210:211], v[208:209], 0, s[100:101]
	v_lshl_add_u64 v[212:213], v[210:211], 0, s[100:101]
	v_lshl_add_u64 v[214:215], v[212:213], 0, s[100:101]
	s_waitcnt lgkmcnt(0)
	s_barrier
	global_load_dword v0, v[6:7], off
	s_mov_b32 s0, 0x8000
	v_add_co_u32_e32 v8, vcc, s0, v6
	s_mov_b32 s0, 0x10000
	s_nop 0
	v_addc_co_u32_e32 v9, vcc, 0, v7, vcc
	global_load_dword v18, v[8:9], off
	v_add_co_u32_e32 v8, vcc, s0, v6
	s_mov_b32 s0, 0x18000
	s_nop 0
	v_addc_co_u32_e32 v9, vcc, 0, v7, vcc
	global_load_dword v22, v[8:9], off
	v_add_co_u32_e32 v8, vcc, s0, v6
	s_mov_b32 s0, 0x20000
	s_nop 0
	v_addc_co_u32_e32 v9, vcc, 0, v7, vcc
	global_load_dword v23, v[8:9], off
	v_add_co_u32_e32 v8, vcc, s0, v6
	s_mov_b32 s0, 0x28000
	s_nop 0
	v_addc_co_u32_e32 v9, vcc, 0, v7, vcc
	global_load_dword v26, v[8:9], off
	v_add_co_u32_e32 v8, vcc, s0, v6
	s_mov_b32 s1, 0x30000
	s_nop 0
	v_addc_co_u32_e32 v9, vcc, 0, v7, vcc
	global_load_dword v27, v[8:9], off
	v_add_co_u32_e32 v8, vcc, s1, v6
	v_lshlrev_b32_e32 v10, 8, v10
	s_nop 0
	v_addc_co_u32_e32 v9, vcc, 0, v7, vcc
	global_load_dword v28, v[8:9], off
	v_lshlrev_b32_e32 v31, 2, v30
	v_add3_u32 v8, 0, v10, v31
	v_add_u32_e32 v32, 0x1800, v8
	ds_read2_b32 v[14:15], v32 offset0:64 offset1:68
	s_mov_b32 s0, 0x38000
	v_add_co_u32_e32 v8, vcc, s0, v6
	s_mov_b32 s0, 0x40000
	s_nop 0
	v_addc_co_u32_e32 v9, vcc, 0, v7, vcc
	global_load_dword v29, v[8:9], off
	v_add_co_u32_e32 v12, vcc, s0, v6
	s_mov_b32 s0, 0x48000
	s_nop 0
	v_addc_co_u32_e32 v13, vcc, 0, v7, vcc
	v_add_co_u32_e32 v20, vcc, s0, v6
	s_mov_b32 s0, 0x50000
	s_nop 0
	v_addc_co_u32_e32 v21, vcc, 0, v7, vcc
	s_waitcnt lgkmcnt(0)
	s_waitcnt vmcnt(7)
	v_mfma_f32_16x16x4_f32 v[8:11], v14, v0, 0
	global_load_dword v0, v[12:13], off
	global_load_dword v33, v[20:21], off
	v_add_co_u32_e32 v20, vcc, s0, v6
	s_mov_b32 s0, 0x58000
	s_nop 0
	v_addc_co_u32_e32 v21, vcc, 0, v7, vcc
	s_waitcnt vmcnt(8)
	v_mfma_f32_16x16x4_f32 v[8:11], v15, v18, v[8:11]
	ds_read2_b32 v[18:19], v32 offset0:72 offset1:76
	global_load_dword v34, v[20:21], off
	v_add_co_u32_e32 v24, vcc, s0, v6
	s_mov_b32 s1, 0x60000
	s_nop 0
	v_addc_co_u32_e32 v25, vcc, 0, v7, vcc
	s_waitcnt lgkmcnt(0)
	s_waitcnt vmcnt(8)
	v_mfma_f32_16x16x4_f32 v[10:13], v18, v22, v[8:11]
	s_nop 1
	ds_read2_b32 v[8:9], v32 offset0:80 offset1:84
	global_load_dword v35, v[24:25], off
	s_mov_b32 s0, 0x68000
	v_readlane_b32 s77, v253, 29
	v_readlane_b32 s78, v253, 30
	v_readlane_b32 s79, v253, 31
	v_readlane_b32 s80, v253, 32
	s_waitcnt vmcnt(8)
	v_mfma_f32_16x16x4_f32 v[10:13], v19, v23, v[10:13]
	v_readlane_b32 s81, v253, 33
	v_readlane_b32 s82, v253, 34
	v_readlane_b32 s83, v253, 35
	v_readlane_b32 s84, v253, 36
	v_readlane_b32 s85, v253, 37
	v_readlane_b32 s86, v253, 38
	v_readlane_b32 s87, v253, 39
	s_waitcnt lgkmcnt(0)
	s_waitcnt vmcnt(7)
; __device__ __forceinline__ void filt_item(const Params& p, int lsel, int tile, float* lds, int wave, float (&colsum)[16], bool flush) {
;     ...
;             for (int s_ = 0; s_ < 16; ++s_) acc = __builtin_amdgcn_mfma_f32_16x16x4f32(av[s_], wp[(size_t)s_ * 4 * 2048], acc, 0, 0, 0);
;             const float dec = fabsf(p.hy_decay[col]); float asum = 0.f;
; #pragma unroll
;             for (int r = 0; r < 4; ++r) { const float tn = (float)(t0 + 4 * g + r) * inv_lm1; acc[r] *= __expf(-tn * dec); asum += fabsf(acc[r]); }
;             *(f32x4*)(filt + (size_t)col * L + t0 + 4 * g) = acc;
;             colsum[ct] += asum;
;             if (flush) { float tot = colsum[ct]; tot += __shfl_xor(tot, 16); tot += __shfl_xor(tot, 32); if (g == 0) atomicAdd(normsum + col, tot); colsum[ct] = 0.f; }
	v_mfma_f32_16x16x4_f32 v[20:23], v8, v26, v[10:13]
	s_nop 0
	v_add_co_u32_e32 v12, vcc, s1, v6
	s_mov_b32 s1, 0x70000
	s_nop 0
	v_addc_co_u32_e32 v13, vcc, 0, v7, vcc
	global_load_dword v36, v[12:13], off
	v_add_co_u32_e32 v24, vcc, s0, v6
	s_mov_b32 s0, 0x78000
	s_nop 0
	v_addc_co_u32_e32 v25, vcc, 0, v7, vcc
	global_load_dword v37, v[24:25], off
	v_add_co_u32_e32 v24, vcc, s1, v6
	v_readlane_b32 s88, v253, 40
	s_nop 0
	v_addc_co_u32_e32 v25, vcc, 0, v7, vcc
	global_load_dword v39, v[24:25], off
	v_readlane_b32 s89, v253, 41
	v_add_co_u32_e32 v26, vcc, s0, v6
	ds_read2_b32 v[10:11], v32 offset0:88 offset1:92
	s_waitcnt vmcnt(9)
	v_mfma_f32_16x16x4_f32 v[20:23], v9, v27, v[20:23]
	v_readlane_b32 s76, v253, 44
	v_addc_co_u32_e32 v27, vcc, 0, v7, vcc
	v_readlane_b32 s77, v253, 45
	global_load_dword v65, v[26:27], off
	ds_read2_b32 v[12:13], v32 offset0:96 offset1:100
	v_lshl_add_u64 v[16:17], s[76:77], 0, v[16:17]
	global_load_dword v38, v[16:17], off
	global_load_dword v216, v[6:7], off offset:64
	global_load_dword v217, v[204:205], off offset:64
	global_load_dword v218, v[206:207], off offset:64
	global_load_dword v219, v[208:209], off offset:64
	global_load_dword v220, v[210:211], off offset:64
	global_load_dword v221, v[212:213], off offset:64
	global_load_dword v222, v[214:215], off offset:64
	global_load_dword v225, v[16:17], off offset:64
	s_waitcnt lgkmcnt(1)
	s_waitcnt vmcnt(18)
	v_mfma_f32_16x16x4_f32 v[20:23], v10, v28, v[20:23]
	v_cvt_f32_u32_e32 v68, s3
	v_cmp_eq_u32_e64 s[0:1], 0, v30
	v_readlane_b32 s78, v253, 46
	v_readlane_b32 s79, v253, 47
	v_div_scale_f32 v70, s[4:5], v68, v68, 1.0
	v_rcp_f32_e32 v71, v70
	s_waitcnt vmcnt(17)
	v_mfma_f32_16x16x4_f32 v[20:23], v11, v29, v[20:23]
	v_div_scale_f32 v72, vcc, 1.0, v68, 1.0
	v_readlane_b32 s80, v253, 48
	v_readlane_b32 s81, v253, 49
	v_readlane_b32 s82, v253, 50
	v_readlane_b32 s83, v253, 51
	v_readlane_b32 s84, v253, 52
	s_waitcnt lgkmcnt(0)
	s_waitcnt vmcnt(16)
	v_mfma_f32_16x16x4_f32 v[22:25], v12, v0, v[20:23]
	s_nop 1
	ds_read2_b32 v[20:21], v32 offset0:104 offset1:108
	v_or_b32_e32 v0, s28, v31
	v_or_b32_e32 v30, 1, v0
	v_or_b32_e32 v31, 2, v0
	v_cvt_f32_i32_e32 v67, v30
	v_fma_f32 v30, -v70, v71, 1.0
	v_cvt_f32_i32_e32 v69, v31
	s_waitcnt vmcnt(15)
	v_mfma_f32_16x16x4_f32 v[26:29], v13, v33, v[22:25]
	ds_read2_b32 v[24:25], v32 offset0:112 offset1:116
	ds_read2_b32 v[22:23], v32 offset0:120 offset1:124
	v_fmac_f32_e32 v71, v30, v71
	v_mul_f32_e32 v73, v72, v71
	v_cvt_f32_i32_e32 v66, v0
	v_or_b32_e32 v0, 3, v0
	v_cvt_f32_i32_e32 v0, v0
	s_waitcnt lgkmcnt(2)
	s_waitcnt vmcnt(14)
	v_mfma_f32_16x16x4_f32 v[26:29], v20, v34, v[26:29]
	v_readlane_b32 s85, v253, 53
	v_readlane_b32 s86, v253, 54
	v_readlane_b32 s87, v253, 55
	v_readlane_b32 s88, v253, 56
	v_readlane_b32 s89, v253, 57
	v_readlane_b32 s90, v253, 58
	v_readlane_b32 s91, v253, 59
	s_waitcnt vmcnt(13)
	v_mfma_f32_16x16x4_f32 v[26:29], v21, v35, v[26:29]
	v_lshlrev_b64 v[34:35], s24, v[2:3]
	v_lshl_add_u64 v[34:35], v[34:35], 2, v[4:5]
	s_waitcnt lgkmcnt(1)
	s_waitcnt vmcnt(12)
	v_mfma_f32_16x16x4_f32 v[30:33], v24, v36, v[26:29]
	s_nop 5
	v_fma_f32 v26, -v70, v73, v72
	v_fmac_f32_e32 v73, v26, v71
	v_fma_f32 v26, -v70, v73, v72
	v_div_fmas_f32 v26, v26, v71, v73
	v_div_fixup_f32 v29, v26, v68, 1.0
	v_mul_f32_e64 v28, v29, -v66
	v_mul_f32_e64 v27, v29, -v67
	s_waitcnt vmcnt(11)
	v_mfma_f32_16x16x4_f32 v[30:33], v25, v37, v[30:33]
	v_mul_f32_e64 v26, v29, -v69
	v_mul_f32_e64 v0, v29, -v0
	s_and_b64 vcc, exec, s[8:9]
	s_waitcnt vmcnt(8)
	v_mul_f32_e64 v29, v28, |v38|
	s_waitcnt lgkmcnt(0)
	v_mfma_f32_16x16x4_f32 v[30:33], v22, v39, v[30:33]
	v_mul_f32_e64 v36, v27, |v38|
	v_mul_f32_e64 v37, v26, |v38|
	v_mul_f32_e64 v38, v0, |v38|
	v_mul_f32_e32 v29, 0x3fb8aa3b, v29
	v_mul_f32_e32 v39, 0x3fb8aa3b, v36
	v_mul_f32_e32 v66, 0x3fb8aa3b, v37
	v_mul_f32_e32 v67, 0x3fb8aa3b, v38
	v_mfma_f32_16x16x4_f32 v[30:33], v23, v65, v[30:33]
	v_exp_f32_e32 v36, v29
	v_exp_f32_e32 v37, v39
	v_exp_f32_e32 v38, v66
	v_exp_f32_e32 v39, v67
	s_nop 5
	v_pk_mul_f32 v[30:31], v[30:31], v[36:37]
	v_pk_mul_f32 v[32:33], v[32:33], v[38:39]
	v_add_f32_e64 v29, |v30|, |v31|
	v_add_f32_e64 v29, |v32|, v29
	v_add_f32_e64 v29, |v33|, v29
	v_add_f32_e32 v64, v64, v29
	global_store_dwordx4 v[34:35], v[30:33], off
	s_cbranch_vccz .LBB0_79
	s_nop 0
	v_and_b32_e32 v30, 64, v48
	v_xor_b32_e32 v29, 16, v48
	v_add_u32_e32 v30, 64, v30
	v_cmp_lt_i32_e32 vcc, v29, v30
	v_xor_b32_e32 v31, 32, v48
	s_nop 0
	v_cndmask_b32_e32 v29, v48, v29, vcc
	v_lshlrev_b32_e32 v29, 2, v29
	ds_bpermute_b32 v29, v29, v64
	v_cmp_lt_i32_e32 vcc, v31, v30
	s_waitcnt lgkmcnt(0)
	v_add_f32_e32 v29, v64, v29
	v_cndmask_b32_e32 v30, v48, v31, vcc
	v_lshlrev_b32_e32 v30, 2, v30
	ds_bpermute_b32 v30, v30, v29
	s_and_saveexec_b64 s[4:5], s[0:1]
	s_cbranch_execz .LBB0_78
	v_lshl_add_u64 v[32:33], v[2:3], 2, s[6:7]
	s_waitcnt lgkmcnt(0)
	v_add_f32_e32 v29, v29, v30
	global_atomic_add_f32 v[32:33], v29, off

; __device__ __forceinline__ void filt_item(const Params& p, int lsel, int tile, float* lds, int wave, float (&colsum)[16], bool flush) {
;     ...
;         for (int ct = 0; ct < 16; ++ct) {
;             const int col = wv * 256 + ct * 16 + l15;
;             const float* wp = p.hy_pos_w3 + (size_t)g * 2048 + col;
;             f32x4 acc = (f32x4){0.f, 0.f, 0.f, 0.f};
; #pragma unroll
;             for (int s_ = 0; s_ < 16; ++s_) acc = __builtin_amdgcn_mfma_f32_16x16x4f32(av[s_], wp[(size_t)s_ * 4 * 2048], acc, 0, 0, 0);
;             const float dec = fabsf(p.hy_decay[col]); float asum = 0.f;
; #pragma unroll
;             for (int r = 0; r < 4; ++r) { const float tn = (float)(t0 + 4 * g + r) * inv_lm1; acc[r] *= __expf(-tn * dec); asum += fabsf(acc[r]); }
;             *(f32x4*)(filt + (size_t)col * L + t0 + 4 * g) = acc;
;             colsum[ct] += asum;
;             if (flush) { float tot = colsum[ct]; tot += __shfl_xor(tot, 16); tot += __shfl_xor(tot, 32); if (g == 0) atomicAdd(normsum + col, tot); colsum[ct] = 0.f; }
.LBB0_79:
	s_waitcnt lgkmcnt(0)
	v_add_co_u32_e32 v34, vcc, 0x38000, v6
	s_waitcnt vmcnt(8)
	v_mfma_f32_16x16x4_f32 v[30:33], v14, v216, 0
	v_addc_co_u32_e32 v35, vcc, 0, v7, vcc
	v_add_co_u32_e32 v36, vcc, 0x40000, v6
	s_nop 1
	v_addc_co_u32_e32 v37, vcc, 0, v7, vcc
	global_load_dword v29, v[34:35], off offset:64
	global_load_dword v69, v[36:37], off offset:64
	s_waitcnt vmcnt(9)
	v_mfma_f32_16x16x4_f32 v[30:33], v15, v217, v[30:33]
	v_add_co_u32_e32 v34, vcc, 0x48000, v6
	s_nop 1
	v_addc_co_u32_e32 v35, vcc, 0, v7, vcc
	s_waitcnt vmcnt(8)
	v_mfma_f32_16x16x4_f32 v[30:33], v18, v218, v[30:33]
	s_waitcnt vmcnt(7)
	v_mfma_f32_16x16x4_f32 v[30:33], v19, v219, v[30:33]
	global_load_dword v65, v[34:35], off offset:64
	v_add_co_u32_e32 v34, vcc, 0x50000, v6
	s_nop 1
	v_addc_co_u32_e32 v35, vcc, 0, v7, vcc
	s_waitcnt vmcnt(7)
	v_mfma_f32_16x16x4_f32 v[30:33], v8, v220, v[30:33]
	global_load_dword v66, v[34:35], off offset:64
	v_add_co_u32_e32 v34, vcc, 0x58000, v6
	s_nop 1
	v_addc_co_u32_e32 v35, vcc, 0, v7, vcc
	s_waitcnt vmcnt(7)
	v_mfma_f32_16x16x4_f32 v[30:33], v9, v221, v[30:33]
	global_load_dword v67, v[34:35], off offset:64
	v_add_co_u32_e32 v34, vcc, 0x60000, v6
	s_nop 1
	v_addc_co_u32_e32 v35, vcc, 0, v7, vcc
	s_waitcnt vmcnt(7)
	v_mfma_f32_16x16x4_f32 v[30:33], v10, v222, v[30:33]
	global_load_dword v68, v[34:35], off offset:64
	v_add_co_u32_e32 v34, vcc, 0x68000, v6
	s_nop 1
	v_addc_co_u32_e32 v35, vcc, 0, v7, vcc
	v_add_co_u32_e32 v36, vcc, 0x70000, v6
	s_waitcnt vmcnt(5)
	v_mfma_f32_16x16x4_f32 v[30:33], v11, v29, v[30:33]
	v_addc_co_u32_e32 v37, vcc, 0, v7, vcc
	v_add_co_u32_e32 v38, vcc, 0x78000, v6
	s_nop 1
	v_addc_co_u32_e32 v39, vcc, 0, v7, vcc
	global_load_dword v29, v[34:35], off offset:64
	s_nop 0
	global_load_dword v36, v[36:37], off offset:64
	s_nop 0
	global_load_dword v38, v[38:39], off offset:64
	s_waitcnt vmcnt(7)
	v_mfma_f32_16x16x4_f32 v[30:33], v12, v69, v[30:33]
	global_load_dword v216, v[6:7], off offset:128
	global_load_dword v217, v[204:205], off offset:128
	global_load_dword v218, v[206:207], off offset:128
	global_load_dword v219, v[208:209], off offset:128
	global_load_dword v220, v[210:211], off offset:128
	global_load_dword v221, v[212:213], off offset:128
	global_load_dword v222, v[214:215], off offset:128
	global_load_dword v224, v[16:17], off offset:128
	v_or_b32_e32 v34, 16, v2
	v_ashrrev_i32_e32 v35, 31, v34
	v_lshlrev_b64 v[34:35], s24, v[34:35]
	v_lshl_add_u64 v[34:35], v[34:35], 2, v[4:5]
	s_andn2_b64 vcc, exec, s[8:9]
	v_mul_f32_e64 v39, v27, |v225|
	s_waitcnt vmcnt(14)
	v_mfma_f32_16x16x4_f32 v[30:33], v13, v65, v[30:33]
	v_mul_f32_e64 v65, v26, |v225|
	s_waitcnt vmcnt(13)
	v_mfma_f32_16x16x4_f32 v[30:33], v20, v66, v[30:33]
	s_waitcnt vmcnt(12)
	v_mfma_f32_16x16x4_f32 v[30:33], v21, v67, v[30:33]
	s_waitcnt vmcnt(11)
	v_mfma_f32_16x16x4_f32 v[30:33], v24, v68, v[30:33]
	s_waitcnt vmcnt(10)
	v_mfma_f32_16x16x4_f32 v[30:33], v25, v29, v[30:33]
	v_cndmask_b32_e64 v29, 0, 1, s[8:9]
	v_cmp_ne_u32_e64 s[4:5], 1, v29
	v_mul_f32_e64 v29, v28, |v225|
	v_mul_f32_e32 v29, 0x3fb8aa3b, v29
	s_waitcnt vmcnt(9)
	v_mfma_f32_16x16x4_f32 v[30:33], v22, v36, v[30:33]
	v_mul_f32_e64 v36, v0, |v225|
	v_mul_f32_e32 v37, 0x3fb8aa3b, v39
	v_mul_f32_e32 v39, 0x3fb8aa3b, v65
	v_mul_f32_e32 v65, 0x3fb8aa3b, v36
	v_exp_f32_e32 v36, v29
	v_exp_f32_e32 v37, v37
	s_waitcnt vmcnt(8)
	v_mfma_f32_16x16x4_f32 v[30:33], v23, v38, v[30:33]
	v_exp_f32_e32 v38, v39
	v_exp_f32_e32 v39, v65
	s_nop 7
	v_pk_mul_f32 v[30:31], v[30:31], v[36:37]
	v_pk_mul_f32 v[32:33], v[32:33], v[38:39]
	v_add_f32_e64 v29, |v30|, |v31|
	v_add_f32_e64 v29, |v32|, v29
	v_add_f32_e64 v29, |v33|, v29
	v_add_f32_e32 v63, v63, v29
	global_store_dwordx4 v[34:35], v[30:33], off
	s_cbranch_vccnz .LBB0_83
	s_nop 0
	v_and_b32_e32 v30, 64, v48
	v_xor_b32_e32 v29, 16, v48
	v_add_u32_e32 v30, 64, v30
	v_cmp_lt_i32_e32 vcc, v29, v30
	v_xor_b32_e32 v31, 32, v48
	s_nop 0
	v_cndmask_b32_e32 v29, v48, v29, vcc
	v_lshlrev_b32_e32 v29, 2, v29
	ds_bpermute_b32 v29, v29, v63
	v_cmp_lt_i32_e32 vcc, v31, v30
	s_waitcnt lgkmcnt(0)
	v_add_f32_e32 v29, v63, v29
	v_cndmask_b32_e32 v30, v48, v31, vcc
	v_lshlrev_b32_e32 v30, 2, v30
	ds_bpermute_b32 v30, v30, v29
	s_and_saveexec_b64 s[8:9], s[0:1]
	s_cbranch_execz .LBB0_82
	v_lshl_add_u64 v[32:33], v[2:3], 2, s[6:7]
	s_waitcnt lgkmcnt(0)
	v_add_f32_e32 v29, v29, v30
	global_atomic_add_f32 v[32:33], v29, off offset:64

; __device__ __forceinline__ void filt_item(const Params& p, int lsel, int tile, float* lds, int wave, float (&colsum)[16], bool flush) {
;     ...
;         for (int ct = 0; ct < 16; ++ct) {
;             const int col = wv * 256 + ct * 16 + l15;
;             const float* wp = p.hy_pos_w3 + (size_t)g * 2048 + col;
;             f32x4 acc = (f32x4){0.f, 0.f, 0.f, 0.f};
; #pragma unroll
;             for (int s_ = 0; s_ < 16; ++s_) acc = __builtin_amdgcn_mfma_f32_16x16x4f32(av[s_], wp[(size_t)s_ * 4 * 2048], acc, 0, 0, 0);
;             const float dec = fabsf(p.hy_decay[col]); float asum = 0.f;
; #pragma unroll
;             for (int r = 0; r < 4; ++r) { const float tn = (float)(t0 + 4 * g + r) * inv_lm1; acc[r] *= __expf(-tn * dec); asum += fabsf(acc[r]); }
;             *(f32x4*)(filt + (size_t)col * L + t0 + 4 * g) = acc;
;             colsum[ct] += asum;
;             if (flush) { float tot = colsum[ct]; tot += __shfl_xor(tot, 16); tot += __shfl_xor(tot, 32); if (g == 0) atomicAdd(normsum + col, tot); colsum[ct] = 0.f; }
.LBB0_83:
	s_waitcnt lgkmcnt(0)
	v_add_co_u32_e32 v34, vcc, 0x38000, v6
	s_waitcnt vmcnt(8)
	v_mfma_f32_16x16x4_f32 v[30:33], v14, v216, 0
	v_addc_co_u32_e32 v35, vcc, 0, v7, vcc
	global_load_dword v29, v[34:35], off offset:128
	v_add_co_u32_e32 v34, vcc, 0x40000, v6
	s_nop 1
	v_addc_co_u32_e32 v35, vcc, 0, v7, vcc
	s_waitcnt vmcnt(8)
	v_mfma_f32_16x16x4_f32 v[30:33], v15, v217, v[30:33]
	global_load_dword v67, v[34:35], off offset:128
	v_add_co_u32_e32 v34, vcc, 0x48000, v6
	s_nop 1
	v_addc_co_u32_e32 v35, vcc, 0, v7, vcc
	s_waitcnt vmcnt(8)
	v_mfma_f32_16x16x4_f32 v[30:33], v18, v218, v[30:33]
	s_waitcnt vmcnt(7)
	v_mfma_f32_16x16x4_f32 v[30:33], v19, v219, v[30:33]
	global_load_dword v38, v[34:35], off offset:128
	v_add_co_u32_e32 v34, vcc, 0x50000, v6
	s_nop 1
	v_addc_co_u32_e32 v35, vcc, 0, v7, vcc
	s_waitcnt vmcnt(7)
	v_mfma_f32_16x16x4_f32 v[30:33], v8, v220, v[30:33]
	global_load_dword v39, v[34:35], off offset:128
	v_add_co_u32_e32 v34, vcc, 0x58000, v6
	s_nop 1
	v_addc_co_u32_e32 v35, vcc, 0, v7, vcc
	s_waitcnt vmcnt(7)
	v_mfma_f32_16x16x4_f32 v[30:33], v9, v221, v[30:33]
	global_load_dword v65, v[34:35], off offset:128
	v_add_co_u32_e32 v34, vcc, 0x60000, v6
	s_nop 1
	v_addc_co_u32_e32 v35, vcc, 0, v7, vcc
	s_waitcnt vmcnt(7)
	v_mfma_f32_16x16x4_f32 v[30:33], v10, v222, v[30:33]
	global_load_dword v66, v[34:35], off offset:128
	v_add_co_u32_e32 v34, vcc, 0x68000, v6
	s_nop 1
	v_addc_co_u32_e32 v35, vcc, 0, v7, vcc
	s_waitcnt vmcnt(5)
	v_mfma_f32_16x16x4_f32 v[30:33], v11, v29, v[30:33]
	global_load_dword v29, v[34:35], off offset:128
	v_add_co_u32_e32 v34, vcc, 0x70000, v6
	s_nop 1
	v_addc_co_u32_e32 v35, vcc, 0, v7, vcc
	v_add_co_u32_e32 v36, vcc, 0x78000, v6
	s_waitcnt vmcnt(5)
	v_mfma_f32_16x16x4_f32 v[30:33], v12, v67, v[30:33]
	v_addc_co_u32_e32 v37, vcc, 0, v7, vcc
	global_load_dword v67, v[34:35], off offset:128
	global_load_dword v68, v[36:37], off offset:128
	v_or_b32_e32 v34, 32, v2
	v_ashrrev_i32_e32 v35, 31, v34
	v_lshlrev_b64 v[34:35], s24, v[34:35]
	v_lshl_add_u64 v[34:35], v[34:35], 2, v[4:5]
	s_and_b64 vcc, exec, s[4:5]
	s_waitcnt vmcnt(6)
	v_mfma_f32_16x16x4_f32 v[30:33], v13, v38, v[30:33]
	s_waitcnt vmcnt(5)
	v_mfma_f32_16x16x4_f32 v[30:33], v20, v39, v[30:33]
	s_waitcnt vmcnt(4)
	v_mfma_f32_16x16x4_f32 v[30:33], v21, v65, v[30:33]
	s_waitcnt vmcnt(3)
	v_mfma_f32_16x16x4_f32 v[30:33], v24, v66, v[30:33]
	s_waitcnt vmcnt(2)
	v_mfma_f32_16x16x4_f32 v[30:33], v25, v29, v[30:33]
	global_load_dword v216, v[6:7], off offset:192
	global_load_dword v217, v[204:205], off offset:192
	global_load_dword v218, v[206:207], off offset:192
	global_load_dword v219, v[208:209], off offset:192
	global_load_dword v220, v[210:211], off offset:192
	global_load_dword v221, v[212:213], off offset:192
	global_load_dword v222, v[214:215], off offset:192
	global_load_dword v225, v[16:17], off offset:192
	v_mul_f32_e64 v36, v28, |v224|
	s_waitcnt vmcnt(9)
	v_mfma_f32_16x16x4_f32 v[30:33], v22, v67, v[30:33]
	v_mul_f32_e64 v37, v27, |v224|
	v_mul_f32_e64 v38, v26, |v224|
	v_mul_f32_e64 v29, v0, |v224|
	v_mul_f32_e32 v36, 0x3fb8aa3b, v36
	v_mul_f32_e32 v37, 0x3fb8aa3b, v37
	v_mul_f32_e32 v38, 0x3fb8aa3b, v38
	v_mul_f32_e32 v29, 0x3fb8aa3b, v29
	s_waitcnt vmcnt(8)
	v_mfma_f32_16x16x4_f32 v[30:33], v23, v68, v[30:33]
	v_exp_f32_e32 v36, v36
	v_exp_f32_e32 v37, v37
	v_exp_f32_e32 v38, v38
	v_exp_f32_e32 v39, v29
	s_nop 5
	v_pk_mul_f32 v[30:31], v[30:31], v[36:37]
	v_pk_mul_f32 v[32:33], v[32:33], v[38:39]
	v_add_f32_e64 v29, |v30|, |v31|
	v_add_f32_e64 v29, |v32|, v29
	v_add_f32_e64 v29, |v33|, v29
	v_add_f32_e32 v62, v62, v29
	global_store_dwordx4 v[34:35], v[30:33], off
	s_cbranch_vccnz .LBB0_87
	s_nop 0
	v_and_b32_e32 v30, 64, v48
	v_xor_b32_e32 v29, 16, v48
	v_add_u32_e32 v30, 64, v30
	v_cmp_lt_i32_e32 vcc, v29, v30
	v_xor_b32_e32 v31, 32, v48
	s_nop 0
	v_cndmask_b32_e32 v29, v48, v29, vcc
	v_lshlrev_b32_e32 v29, 2, v29
	ds_bpermute_b32 v29, v29, v62
	v_cmp_lt_i32_e32 vcc, v31, v30
	s_waitcnt lgkmcnt(0)
	v_add_f32_e32 v29, v62, v29
	v_cndmask_b32_e32 v30, v48, v31, vcc
	v_lshlrev_b32_e32 v30, 2, v30
	ds_bpermute_b32 v30, v30, v29
	s_and_saveexec_b64 s[8:9], s[0:1]
	s_cbranch_execz .LBB0_86
	v_lshl_add_u64 v[32:33], v[2:3], 2, s[6:7]
	s_waitcnt lgkmcnt(0)
	v_add_f32_e32 v29, v29, v30
	global_atomic_add_f32 v[32:33], v29, off offset:128

; __device__ __forceinline__ void filt_item(const Params& p, int lsel, int tile, float* lds, int wave, float (&colsum)[16], bool flush) {
;     ...
;         for (int ct = 0; ct < 16; ++ct) {
;             const int col = wv * 256 + ct * 16 + l15;
;             const float* wp = p.hy_pos_w3 + (size_t)g * 2048 + col;
;             f32x4 acc = (f32x4){0.f, 0.f, 0.f, 0.f};
; #pragma unroll
;             for (int s_ = 0; s_ < 16; ++s_) acc = __builtin_amdgcn_mfma_f32_16x16x4f32(av[s_], wp[(size_t)s_ * 4 * 2048], acc, 0, 0, 0);
;             const float dec = fabsf(p.hy_decay[col]); float asum = 0.f;
; #pragma unroll
;             for (int r = 0; r < 4; ++r) { const float tn = (float)(t0 + 4 * g + r) * inv_lm1; acc[r] *= __expf(-tn * dec); asum += fabsf(acc[r]); }
;             *(f32x4*)(filt + (size_t)col * L + t0 + 4 * g) = acc;
;             colsum[ct] += asum;
;             if (flush) { float tot = colsum[ct]; tot += __shfl_xor(tot, 16); tot += __shfl_xor(tot, 32); if (g == 0) atomicAdd(normsum + col, tot); colsum[ct] = 0.f; }
.LBB0_87:
	s_waitcnt lgkmcnt(0)
	v_add_co_u32_e32 v34, vcc, 0x38000, v6
	s_waitcnt vmcnt(8)
	v_mfma_f32_16x16x4_f32 v[30:33], v14, v216, 0
	v_addc_co_u32_e32 v35, vcc, 0, v7, vcc
	global_load_dword v29, v[34:35], off offset:192
	v_add_co_u32_e32 v34, vcc, 0x40000, v6
	s_nop 1
	v_addc_co_u32_e32 v35, vcc, 0, v7, vcc
	s_waitcnt vmcnt(8)
	v_mfma_f32_16x16x4_f32 v[30:33], v15, v217, v[30:33]
	global_load_dword v67, v[34:35], off offset:192
	v_add_co_u32_e32 v34, vcc, 0x48000, v6
	s_nop 1
	v_addc_co_u32_e32 v35, vcc, 0, v7, vcc
	s_waitcnt vmcnt(8)
	v_mfma_f32_16x16x4_f32 v[30:33], v18, v218, v[30:33]
	s_waitcnt vmcnt(7)
	v_mfma_f32_16x16x4_f32 v[30:33], v19, v219, v[30:33]
	global_load_dword v38, v[34:35], off offset:192
	v_add_co_u32_e32 v34, vcc, 0x50000, v6
	s_nop 1
	v_addc_co_u32_e32 v35, vcc, 0, v7, vcc
	s_waitcnt vmcnt(7)
	v_mfma_f32_16x16x4_f32 v[30:33], v8, v220, v[30:33]
	global_load_dword v39, v[34:35], off offset:192
	v_add_co_u32_e32 v34, vcc, 0x58000, v6
	s_nop 1
	v_addc_co_u32_e32 v35, vcc, 0, v7, vcc
	s_waitcnt vmcnt(7)
	v_mfma_f32_16x16x4_f32 v[30:33], v9, v221, v[30:33]
	global_load_dword v65, v[34:35], off offset:192
	v_add_co_u32_e32 v34, vcc, 0x60000, v6
	s_nop 1
	v_addc_co_u32_e32 v35, vcc, 0, v7, vcc
	s_waitcnt vmcnt(7)
	v_mfma_f32_16x16x4_f32 v[30:33], v10, v222, v[30:33]
	global_load_dword v66, v[34:35], off offset:192
	v_add_co_u32_e32 v34, vcc, 0x68000, v6
	s_nop 1
	v_addc_co_u32_e32 v35, vcc, 0, v7, vcc
	s_waitcnt vmcnt(5)
	v_mfma_f32_16x16x4_f32 v[30:33], v11, v29, v[30:33]
	global_load_dword v29, v[34:35], off offset:192
	v_add_co_u32_e32 v34, vcc, 0x70000, v6
	s_nop 1
	v_addc_co_u32_e32 v35, vcc, 0, v7, vcc
	v_add_co_u32_e32 v36, vcc, 0x78000, v6
	s_waitcnt vmcnt(5)
	v_mfma_f32_16x16x4_f32 v[30:33], v12, v67, v[30:33]
	v_addc_co_u32_e32 v37, vcc, 0, v7, vcc
	global_load_dword v67, v[34:35], off offset:192
	global_load_dword v68, v[36:37], off offset:192
	v_or_b32_e32 v34, 48, v2
	v_ashrrev_i32_e32 v35, 31, v34
	v_lshlrev_b64 v[34:35], s24, v[34:35]
	v_lshl_add_u64 v[34:35], v[34:35], 2, v[4:5]
	s_and_b64 vcc, exec, s[4:5]
	s_waitcnt vmcnt(6)
	v_mfma_f32_16x16x4_f32 v[30:33], v13, v38, v[30:33]
	s_waitcnt vmcnt(5)
	v_mfma_f32_16x16x4_f32 v[30:33], v20, v39, v[30:33]
	s_waitcnt vmcnt(4)
	v_mfma_f32_16x16x4_f32 v[30:33], v21, v65, v[30:33]
	s_waitcnt vmcnt(3)
	v_mfma_f32_16x16x4_f32 v[30:33], v24, v66, v[30:33]
	s_waitcnt vmcnt(2)
	v_mfma_f32_16x16x4_f32 v[30:33], v25, v29, v[30:33]
	global_load_dword v216, v[6:7], off offset:256
	global_load_dword v217, v[204:205], off offset:256
	global_load_dword v218, v[206:207], off offset:256
	global_load_dword v219, v[208:209], off offset:256
	global_load_dword v220, v[210:211], off offset:256
	global_load_dword v221, v[212:213], off offset:256
	global_load_dword v222, v[214:215], off offset:256
	global_load_dword v224, v[16:17], off offset:256
	v_mul_f32_e64 v36, v28, |v225|
	s_waitcnt vmcnt(9)
	v_mfma_f32_16x16x4_f32 v[30:33], v22, v67, v[30:33]
	v_mul_f32_e64 v37, v27, |v225|
	v_mul_f32_e64 v38, v26, |v225|
	v_mul_f32_e64 v29, v0, |v225|
	v_mul_f32_e32 v36, 0x3fb8aa3b, v36
	v_mul_f32_e32 v37, 0x3fb8aa3b, v37
	v_mul_f32_e32 v38, 0x3fb8aa3b, v38
	v_mul_f32_e32 v29, 0x3fb8aa3b, v29
	s_waitcnt vmcnt(8)
	v_mfma_f32_16x16x4_f32 v[30:33], v23, v68, v[30:33]
	v_exp_f32_e32 v36, v36
	v_exp_f32_e32 v37, v37
	v_exp_f32_e32 v38, v38
	v_exp_f32_e32 v39, v29
	s_nop 5
	v_pk_mul_f32 v[30:31], v[30:31], v[36:37]
	v_pk_mul_f32 v[32:33], v[32:33], v[38:39]
	v_add_f32_e64 v29, |v30|, |v31|
	v_add_f32_e64 v29, |v32|, v29
	v_add_f32_e64 v29, |v33|, v29
	v_add_f32_e32 v61, v61, v29
	global_store_dwordx4 v[34:35], v[30:33], off
	s_cbranch_vccnz .LBB0_91
	s_nop 0
	v_and_b32_e32 v30, 64, v48
	v_xor_b32_e32 v29, 16, v48
	v_add_u32_e32 v30, 64, v30
	v_cmp_lt_i32_e32 vcc, v29, v30
	v_xor_b32_e32 v31, 32, v48
	s_nop 0
	v_cndmask_b32_e32 v29, v48, v29, vcc
	v_lshlrev_b32_e32 v29, 2, v29
	ds_bpermute_b32 v29, v29, v61
	v_cmp_lt_i32_e32 vcc, v31, v30
	s_waitcnt lgkmcnt(0)
	v_add_f32_e32 v29, v61, v29
	v_cndmask_b32_e32 v30, v48, v31, vcc
	v_lshlrev_b32_e32 v30, 2, v30
	ds_bpermute_b32 v30, v30, v29
	s_and_saveexec_b64 s[8:9], s[0:1]
	s_cbranch_execz .LBB0_90
	v_lshl_add_u64 v[32:33], v[2:3], 2, s[6:7]
	s_waitcnt lgkmcnt(0)
	v_add_f32_e32 v29, v29, v30
	global_atomic_add_f32 v[32:33], v29, off offset:192

; __device__ __forceinline__ void filt_item(const Params& p, int lsel, int tile, float* lds, int wave, float (&colsum)[16], bool flush) {
;     ...
;         for (int ct = 0; ct < 16; ++ct) {
;             const int col = wv * 256 + ct * 16 + l15;
;             const float* wp = p.hy_pos_w3 + (size_t)g * 2048 + col;
;             f32x4 acc = (f32x4){0.f, 0.f, 0.f, 0.f};
; #pragma unroll
;             for (int s_ = 0; s_ < 16; ++s_) acc = __builtin_amdgcn_mfma_f32_16x16x4f32(av[s_], wp[(size_t)s_ * 4 * 2048], acc, 0, 0, 0);
;             const float dec = fabsf(p.hy_decay[col]); float asum = 0.f;
; #pragma unroll
;             for (int r = 0; r < 4; ++r) { const float tn = (float)(t0 + 4 * g + r) * inv_lm1; acc[r] *= __expf(-tn * dec); asum += fabsf(acc[r]); }
;             *(f32x4*)(filt + (size_t)col * L + t0 + 4 * g) = acc;
;             colsum[ct] += asum;
;             if (flush) { float tot = colsum[ct]; tot += __shfl_xor(tot, 16); tot += __shfl_xor(tot, 32); if (g == 0) atomicAdd(normsum + col, tot); colsum[ct] = 0.f; }
.LBB0_91:
	s_waitcnt lgkmcnt(0)
	v_add_co_u32_e32 v34, vcc, 0x38000, v6
	s_waitcnt vmcnt(8)
	v_mfma_f32_16x16x4_f32 v[30:33], v14, v216, 0
	v_addc_co_u32_e32 v35, vcc, 0, v7, vcc
	global_load_dword v29, v[34:35], off offset:256
	v_add_co_u32_e32 v34, vcc, 0x40000, v6
	s_nop 1
	v_addc_co_u32_e32 v35, vcc, 0, v7, vcc
	s_waitcnt vmcnt(8)
	v_mfma_f32_16x16x4_f32 v[30:33], v15, v217, v[30:33]
	global_load_dword v67, v[34:35], off offset:256
	v_add_co_u32_e32 v34, vcc, 0x48000, v6
	s_nop 1
	v_addc_co_u32_e32 v35, vcc, 0, v7, vcc
	s_waitcnt vmcnt(8)
	v_mfma_f32_16x16x4_f32 v[30:33], v18, v218, v[30:33]
	s_waitcnt vmcnt(7)
	v_mfma_f32_16x16x4_f32 v[30:33], v19, v219, v[30:33]
	global_load_dword v38, v[34:35], off offset:256
	v_add_co_u32_e32 v34, vcc, 0x50000, v6
	s_nop 1
	v_addc_co_u32_e32 v35, vcc, 0, v7, vcc
	s_waitcnt vmcnt(7)
	v_mfma_f32_16x16x4_f32 v[30:33], v8, v220, v[30:33]
	global_load_dword v39, v[34:35], off offset:256
	v_add_co_u32_e32 v34, vcc, 0x58000, v6
	s_nop 1
	v_addc_co_u32_e32 v35, vcc, 0, v7, vcc
	s_waitcnt vmcnt(7)
	v_mfma_f32_16x16x4_f32 v[30:33], v9, v221, v[30:33]
	global_load_dword v65, v[34:35], off offset:256
	v_add_co_u32_e32 v34, vcc, 0x60000, v6
	s_nop 1
	v_addc_co_u32_e32 v35, vcc, 0, v7, vcc
	s_waitcnt vmcnt(7)
	v_mfma_f32_16x16x4_f32 v[30:33], v10, v222, v[30:33]
	global_load_dword v66, v[34:35], off offset:256
	v_add_co_u32_e32 v34, vcc, 0x68000, v6
	s_nop 1
	v_addc_co_u32_e32 v35, vcc, 0, v7, vcc
	s_waitcnt vmcnt(5)
	v_mfma_f32_16x16x4_f32 v[30:33], v11, v29, v[30:33]
	global_load_dword v29, v[34:35], off offset:256
	v_add_co_u32_e32 v34, vcc, 0x70000, v6
	s_nop 1
	v_addc_co_u32_e32 v35, vcc, 0, v7, vcc
	v_add_co_u32_e32 v36, vcc, 0x78000, v6
	s_waitcnt vmcnt(5)
	v_mfma_f32_16x16x4_f32 v[30:33], v12, v67, v[30:33]
	v_addc_co_u32_e32 v37, vcc, 0, v7, vcc
	global_load_dword v67, v[34:35], off offset:256
	global_load_dword v68, v[36:37], off offset:256
	v_or_b32_e32 v34, 64, v2
	v_ashrrev_i32_e32 v35, 31, v34
	v_lshlrev_b64 v[34:35], s24, v[34:35]
	v_lshl_add_u64 v[34:35], v[34:35], 2, v[4:5]
	s_and_b64 vcc, exec, s[4:5]
	s_waitcnt vmcnt(6)
	v_mfma_f32_16x16x4_f32 v[30:33], v13, v38, v[30:33]
	s_waitcnt vmcnt(5)
	v_mfma_f32_16x16x4_f32 v[30:33], v20, v39, v[30:33]
	s_waitcnt vmcnt(4)
	v_mfma_f32_16x16x4_f32 v[30:33], v21, v65, v[30:33]
	s_waitcnt vmcnt(3)
	v_mfma_f32_16x16x4_f32 v[30:33], v24, v66, v[30:33]
	s_waitcnt vmcnt(2)
	v_mfma_f32_16x16x4_f32 v[30:33], v25, v29, v[30:33]
	global_load_dword v216, v[6:7], off offset:320
	global_load_dword v217, v[204:205], off offset:320
	global_load_dword v218, v[206:207], off offset:320
	global_load_dword v219, v[208:209], off offset:320
	global_load_dword v220, v[210:211], off offset:320
	global_load_dword v221, v[212:213], off offset:320
	global_load_dword v222, v[214:215], off offset:320
	global_load_dword v225, v[16:17], off offset:320
	v_mul_f32_e64 v36, v28, |v224|
	s_waitcnt vmcnt(9)
	v_mfma_f32_16x16x4_f32 v[30:33], v22, v67, v[30:33]
	v_mul_f32_e64 v37, v27, |v224|
	v_mul_f32_e64 v38, v26, |v224|
	v_mul_f32_e64 v29, v0, |v224|
	v_mul_f32_e32 v36, 0x3fb8aa3b, v36
	v_mul_f32_e32 v37, 0x3fb8aa3b, v37
	v_mul_f32_e32 v38, 0x3fb8aa3b, v38
	v_mul_f32_e32 v29, 0x3fb8aa3b, v29
	s_waitcnt vmcnt(8)
	v_mfma_f32_16x16x4_f32 v[30:33], v23, v68, v[30:33]
	v_exp_f32_e32 v36, v36
	v_exp_f32_e32 v37, v37
	v_exp_f32_e32 v38, v38
	v_exp_f32_e32 v39, v29
	s_nop 5
	v_pk_mul_f32 v[30:31], v[30:31], v[36:37]
	v_pk_mul_f32 v[32:33], v[32:33], v[38:39]
	v_add_f32_e64 v29, |v30|, |v31|
	v_add_f32_e64 v29, |v32|, v29
	v_add_f32_e64 v29, |v33|, v29
	v_add_f32_e32 v60, v60, v29
	global_store_dwordx4 v[34:35], v[30:33], off
	s_cbranch_vccnz .LBB0_95
	s_nop 0
	v_and_b32_e32 v30, 64, v48
	v_xor_b32_e32 v29, 16, v48
	v_add_u32_e32 v30, 64, v30
	v_cmp_lt_i32_e32 vcc, v29, v30
	v_xor_b32_e32 v31, 32, v48
	s_nop 0
	v_cndmask_b32_e32 v29, v48, v29, vcc
	v_lshlrev_b32_e32 v29, 2, v29
	ds_bpermute_b32 v29, v29, v60
	v_cmp_lt_i32_e32 vcc, v31, v30
	s_waitcnt lgkmcnt(0)
	v_add_f32_e32 v29, v60, v29
	v_cndmask_b32_e32 v30, v48, v31, vcc
	v_lshlrev_b32_e32 v30, 2, v30
	ds_bpermute_b32 v30, v30, v29
	s_and_saveexec_b64 s[8:9], s[0:1]
	s_cbranch_execz .LBB0_94
	v_lshl_add_u64 v[32:33], v[2:3], 2, s[6:7]
	s_waitcnt lgkmcnt(0)
	v_add_f32_e32 v29, v29, v30
	global_atomic_add_f32 v[32:33], v29, off offset:256

; __device__ __forceinline__ void filt_item(const Params& p, int lsel, int tile, float* lds, int wave, float (&colsum)[16], bool flush) {
;     ...
;         for (int ct = 0; ct < 16; ++ct) {
;             const int col = wv * 256 + ct * 16 + l15;
;             const float* wp = p.hy_pos_w3 + (size_t)g * 2048 + col;
;             f32x4 acc = (f32x4){0.f, 0.f, 0.f, 0.f};
; #pragma unroll
;             for (int s_ = 0; s_ < 16; ++s_) acc = __builtin_amdgcn_mfma_f32_16x16x4f32(av[s_], wp[(size_t)s_ * 4 * 2048], acc, 0, 0, 0);
;             const float dec = fabsf(p.hy_decay[col]); float asum = 0.f;
; #pragma unroll
;             for (int r = 0; r < 4; ++r) { const float tn = (float)(t0 + 4 * g + r) * inv_lm1; acc[r] *= __expf(-tn * dec); asum += fabsf(acc[r]); }
;             *(f32x4*)(filt + (size_t)col * L + t0 + 4 * g) = acc;
;             colsum[ct] += asum;
;             if (flush) { float tot = colsum[ct]; tot += __shfl_xor(tot, 16); tot += __shfl_xor(tot, 32); if (g == 0) atomicAdd(normsum + col, tot); colsum[ct] = 0.f; }
.LBB0_95:
	s_waitcnt lgkmcnt(0)
	v_add_co_u32_e32 v34, vcc, 0x38000, v6
	s_waitcnt vmcnt(8)
	v_mfma_f32_16x16x4_f32 v[30:33], v14, v216, 0
	v_addc_co_u32_e32 v35, vcc, 0, v7, vcc
	global_load_dword v29, v[34:35], off offset:320
	v_add_co_u32_e32 v34, vcc, 0x40000, v6
	s_nop 1
	v_addc_co_u32_e32 v35, vcc, 0, v7, vcc
	s_waitcnt vmcnt(8)
	v_mfma_f32_16x16x4_f32 v[30:33], v15, v217, v[30:33]
	global_load_dword v67, v[34:35], off offset:320
	v_add_co_u32_e32 v34, vcc, 0x48000, v6
	s_nop 1
	v_addc_co_u32_e32 v35, vcc, 0, v7, vcc
	s_waitcnt vmcnt(8)
	v_mfma_f32_16x16x4_f32 v[30:33], v18, v218, v[30:33]
	s_waitcnt vmcnt(7)
	v_mfma_f32_16x16x4_f32 v[30:33], v19, v219, v[30:33]
	global_load_dword v38, v[34:35], off offset:320
	v_add_co_u32_e32 v34, vcc, 0x50000, v6
	s_nop 1
	v_addc_co_u32_e32 v35, vcc, 0, v7, vcc
	s_waitcnt vmcnt(7)
	v_mfma_f32_16x16x4_f32 v[30:33], v8, v220, v[30:33]
	global_load_dword v39, v[34:35], off offset:320
	v_add_co_u32_e32 v34, vcc, 0x58000, v6
	s_nop 1
	v_addc_co_u32_e32 v35, vcc, 0, v7, vcc
	s_waitcnt vmcnt(7)
	v_mfma_f32_16x16x4_f32 v[30:33], v9, v221, v[30:33]
	global_load_dword v65, v[34:35], off offset:320
	v_add_co_u32_e32 v34, vcc, 0x60000, v6
	s_nop 1
	v_addc_co_u32_e32 v35, vcc, 0, v7, vcc
	s_waitcnt vmcnt(7)
	v_mfma_f32_16x16x4_f32 v[30:33], v10, v222, v[30:33]
	global_load_dword v66, v[34:35], off offset:320
	v_add_co_u32_e32 v34, vcc, 0x68000, v6
	s_nop 1
	v_addc_co_u32_e32 v35, vcc, 0, v7, vcc
	s_waitcnt vmcnt(5)
	v_mfma_f32_16x16x4_f32 v[30:33], v11, v29, v[30:33]
	global_load_dword v29, v[34:35], off offset:320
	v_add_co_u32_e32 v34, vcc, 0x70000, v6
	s_nop 1
	v_addc_co_u32_e32 v35, vcc, 0, v7, vcc
	v_add_co_u32_e32 v36, vcc, 0x78000, v6
	s_waitcnt vmcnt(5)
	v_mfma_f32_16x16x4_f32 v[30:33], v12, v67, v[30:33]
	v_addc_co_u32_e32 v37, vcc, 0, v7, vcc
	global_load_dword v67, v[34:35], off offset:320
	global_load_dword v68, v[36:37], off offset:320
	v_or_b32_e32 v34, 0x50, v2
	v_ashrrev_i32_e32 v35, 31, v34
	v_lshlrev_b64 v[34:35], s24, v[34:35]
	v_lshl_add_u64 v[34:35], v[34:35], 2, v[4:5]
	s_and_b64 vcc, exec, s[4:5]
	s_waitcnt vmcnt(6)
	v_mfma_f32_16x16x4_f32 v[30:33], v13, v38, v[30:33]
	s_waitcnt vmcnt(5)
	v_mfma_f32_16x16x4_f32 v[30:33], v20, v39, v[30:33]
	s_waitcnt vmcnt(4)
	v_mfma_f32_16x16x4_f32 v[30:33], v21, v65, v[30:33]
	s_waitcnt vmcnt(3)
	v_mfma_f32_16x16x4_f32 v[30:33], v24, v66, v[30:33]
	s_waitcnt vmcnt(2)
	v_mfma_f32_16x16x4_f32 v[30:33], v25, v29, v[30:33]
	global_load_dword v216, v[6:7], off offset:384
	global_load_dword v217, v[204:205], off offset:384
	global_load_dword v218, v[206:207], off offset:384
	global_load_dword v219, v[208:209], off offset:384
	global_load_dword v220, v[210:211], off offset:384
	global_load_dword v221, v[212:213], off offset:384
	global_load_dword v222, v[214:215], off offset:384
	global_load_dword v224, v[16:17], off offset:384
	v_mul_f32_e64 v36, v28, |v225|
	s_waitcnt vmcnt(9)
	v_mfma_f32_16x16x4_f32 v[30:33], v22, v67, v[30:33]
	v_mul_f32_e64 v37, v27, |v225|
	v_mul_f32_e64 v38, v26, |v225|
	v_mul_f32_e64 v29, v0, |v225|
	v_mul_f32_e32 v36, 0x3fb8aa3b, v36
	v_mul_f32_e32 v37, 0x3fb8aa3b, v37
	v_mul_f32_e32 v38, 0x3fb8aa3b, v38
	v_mul_f32_e32 v29, 0x3fb8aa3b, v29
	s_waitcnt vmcnt(8)
	v_mfma_f32_16x16x4_f32 v[30:33], v23, v68, v[30:33]
	v_exp_f32_e32 v36, v36
	v_exp_f32_e32 v37, v37
	v_exp_f32_e32 v38, v38
	v_exp_f32_e32 v39, v29
	s_nop 5
	v_pk_mul_f32 v[30:31], v[30:31], v[36:37]
	v_pk_mul_f32 v[32:33], v[32:33], v[38:39]
	v_add_f32_e64 v29, |v30|, |v31|
	v_add_f32_e64 v29, |v32|, v29
	v_add_f32_e64 v29, |v33|, v29
	v_add_f32_e32 v59, v59, v29
	global_store_dwordx4 v[34:35], v[30:33], off
	s_cbranch_vccnz .LBB0_99
	s_nop 0
	v_and_b32_e32 v30, 64, v48
	v_xor_b32_e32 v29, 16, v48
	v_add_u32_e32 v30, 64, v30
	v_cmp_lt_i32_e32 vcc, v29, v30
	v_xor_b32_e32 v31, 32, v48
	s_nop 0
	v_cndmask_b32_e32 v29, v48, v29, vcc
	v_lshlrev_b32_e32 v29, 2, v29
	ds_bpermute_b32 v29, v29, v59
	v_cmp_lt_i32_e32 vcc, v31, v30
	s_waitcnt lgkmcnt(0)
	v_add_f32_e32 v29, v59, v29
	v_cndmask_b32_e32 v30, v48, v31, vcc
	v_lshlrev_b32_e32 v30, 2, v30
	ds_bpermute_b32 v30, v30, v29
	s_and_saveexec_b64 s[8:9], s[0:1]
	s_cbranch_execz .LBB0_98
	v_lshl_add_u64 v[32:33], v[2:3], 2, s[6:7]
	s_waitcnt lgkmcnt(0)
	v_add_f32_e32 v29, v29, v30
	global_atomic_add_f32 v[32:33], v29, off offset:320

; __device__ __forceinline__ void filt_item(const Params& p, int lsel, int tile, float* lds, int wave, float (&colsum)[16], bool flush) {
;     ...
;         for (int ct = 0; ct < 16; ++ct) {
;             const int col = wv * 256 + ct * 16 + l15;
;             const float* wp = p.hy_pos_w3 + (size_t)g * 2048 + col;
;             f32x4 acc = (f32x4){0.f, 0.f, 0.f, 0.f};
; #pragma unroll
;             for (int s_ = 0; s_ < 16; ++s_) acc = __builtin_amdgcn_mfma_f32_16x16x4f32(av[s_], wp[(size_t)s_ * 4 * 2048], acc, 0, 0, 0);
;             const float dec = fabsf(p.hy_decay[col]); float asum = 0.f;
; #pragma unroll
;             for (int r = 0; r < 4; ++r) { const float tn = (float)(t0 + 4 * g + r) * inv_lm1; acc[r] *= __expf(-tn * dec); asum += fabsf(acc[r]); }
;             *(f32x4*)(filt + (size_t)col * L + t0 + 4 * g) = acc;
;             colsum[ct] += asum;
;             if (flush) { float tot = colsum[ct]; tot += __shfl_xor(tot, 16); tot += __shfl_xor(tot, 32); if (g == 0) atomicAdd(normsum + col, tot); colsum[ct] = 0.f; }
.LBB0_99:
	s_waitcnt lgkmcnt(0)
	v_add_co_u32_e32 v34, vcc, 0x38000, v6
	s_waitcnt vmcnt(8)
	v_mfma_f32_16x16x4_f32 v[30:33], v14, v216, 0
	v_addc_co_u32_e32 v35, vcc, 0, v7, vcc
	global_load_dword v29, v[34:35], off offset:384
	v_add_co_u32_e32 v34, vcc, 0x40000, v6
	s_nop 1
	v_addc_co_u32_e32 v35, vcc, 0, v7, vcc
	s_waitcnt vmcnt(8)
	v_mfma_f32_16x16x4_f32 v[30:33], v15, v217, v[30:33]
	global_load_dword v67, v[34:35], off offset:384
	v_add_co_u32_e32 v34, vcc, 0x48000, v6
	s_nop 1
	v_addc_co_u32_e32 v35, vcc, 0, v7, vcc
	s_waitcnt vmcnt(8)
	v_mfma_f32_16x16x4_f32 v[30:33], v18, v218, v[30:33]
	s_waitcnt vmcnt(7)
	v_mfma_f32_16x16x4_f32 v[30:33], v19, v219, v[30:33]
	global_load_dword v38, v[34:35], off offset:384
	v_add_co_u32_e32 v34, vcc, 0x50000, v6
	s_nop 1
	v_addc_co_u32_e32 v35, vcc, 0, v7, vcc
	s_waitcnt vmcnt(7)
	v_mfma_f32_16x16x4_f32 v[30:33], v8, v220, v[30:33]
	global_load_dword v39, v[34:35], off offset:384
	v_add_co_u32_e32 v34, vcc, 0x58000, v6
	s_nop 1
	v_addc_co_u32_e32 v35, vcc, 0, v7, vcc
	s_waitcnt vmcnt(7)
	v_mfma_f32_16x16x4_f32 v[30:33], v9, v221, v[30:33]
	global_load_dword v65, v[34:35], off offset:384
	v_add_co_u32_e32 v34, vcc, 0x60000, v6
	s_nop 1
	v_addc_co_u32_e32 v35, vcc, 0, v7, vcc
	s_waitcnt vmcnt(7)
	v_mfma_f32_16x16x4_f32 v[30:33], v10, v222, v[30:33]
	global_load_dword v66, v[34:35], off offset:384
	v_add_co_u32_e32 v34, vcc, 0x68000, v6
	s_nop 1
	v_addc_co_u32_e32 v35, vcc, 0, v7, vcc
	s_waitcnt vmcnt(5)
	v_mfma_f32_16x16x4_f32 v[30:33], v11, v29, v[30:33]
	global_load_dword v29, v[34:35], off offset:384
	v_add_co_u32_e32 v34, vcc, 0x70000, v6
	s_nop 1
	v_addc_co_u32_e32 v35, vcc, 0, v7, vcc
	v_add_co_u32_e32 v36, vcc, 0x78000, v6
	s_waitcnt vmcnt(5)
	v_mfma_f32_16x16x4_f32 v[30:33], v12, v67, v[30:33]
	v_addc_co_u32_e32 v37, vcc, 0, v7, vcc
	global_load_dword v67, v[34:35], off offset:384
	global_load_dword v68, v[36:37], off offset:384
	v_or_b32_e32 v34, 0x60, v2
	v_ashrrev_i32_e32 v35, 31, v34
	v_lshlrev_b64 v[34:35], s24, v[34:35]
	v_lshl_add_u64 v[34:35], v[34:35], 2, v[4:5]
	s_and_b64 vcc, exec, s[4:5]
	s_waitcnt vmcnt(6)
	v_mfma_f32_16x16x4_f32 v[30:33], v13, v38, v[30:33]
	s_waitcnt vmcnt(5)
	v_mfma_f32_16x16x4_f32 v[30:33], v20, v39, v[30:33]
	s_waitcnt vmcnt(4)
	v_mfma_f32_16x16x4_f32 v[30:33], v21, v65, v[30:33]
	s_waitcnt vmcnt(3)
	v_mfma_f32_16x16x4_f32 v[30:33], v24, v66, v[30:33]
	s_waitcnt vmcnt(2)
	v_mfma_f32_16x16x4_f32 v[30:33], v25, v29, v[30:33]
	global_load_dword v216, v[6:7], off offset:448
	global_load_dword v217, v[204:205], off offset:448
	global_load_dword v218, v[206:207], off offset:448
	global_load_dword v219, v[208:209], off offset:448
	global_load_dword v220, v[210:211], off offset:448
	global_load_dword v221, v[212:213], off offset:448
	global_load_dword v222, v[214:215], off offset:448
	global_load_dword v225, v[16:17], off offset:448
	v_mul_f32_e64 v36, v28, |v224|
	s_waitcnt vmcnt(9)
	v_mfma_f32_16x16x4_f32 v[30:33], v22, v67, v[30:33]
	v_mul_f32_e64 v37, v27, |v224|
	v_mul_f32_e64 v38, v26, |v224|
	v_mul_f32_e64 v29, v0, |v224|
	v_mul_f32_e32 v36, 0x3fb8aa3b, v36
	v_mul_f32_e32 v37, 0x3fb8aa3b, v37
	v_mul_f32_e32 v38, 0x3fb8aa3b, v38
	v_mul_f32_e32 v29, 0x3fb8aa3b, v29
	s_waitcnt vmcnt(8)
	v_mfma_f32_16x16x4_f32 v[30:33], v23, v68, v[30:33]
	v_exp_f32_e32 v36, v36
	v_exp_f32_e32 v37, v37
	v_exp_f32_e32 v38, v38
	v_exp_f32_e32 v39, v29
	s_nop 5
	v_pk_mul_f32 v[30:31], v[30:31], v[36:37]
	v_pk_mul_f32 v[32:33], v[32:33], v[38:39]
	v_add_f32_e64 v29, |v30|, |v31|
	v_add_f32_e64 v29, |v32|, v29
	v_add_f32_e64 v29, |v33|, v29
	v_add_f32_e32 v58, v58, v29
	global_store_dwordx4 v[34:35], v[30:33], off
	s_cbranch_vccnz .LBB0_103
	s_nop 0
	v_and_b32_e32 v30, 64, v48
	v_xor_b32_e32 v29, 16, v48
	v_add_u32_e32 v30, 64, v30
	v_cmp_lt_i32_e32 vcc, v29, v30
	v_xor_b32_e32 v31, 32, v48
	s_nop 0
	v_cndmask_b32_e32 v29, v48, v29, vcc
	v_lshlrev_b32_e32 v29, 2, v29
	ds_bpermute_b32 v29, v29, v58
	v_cmp_lt_i32_e32 vcc, v31, v30
	s_waitcnt lgkmcnt(0)
	v_add_f32_e32 v29, v58, v29
	v_cndmask_b32_e32 v30, v48, v31, vcc
	v_lshlrev_b32_e32 v30, 2, v30
	ds_bpermute_b32 v30, v30, v29
	s_and_saveexec_b64 s[8:9], s[0:1]
	s_cbranch_execz .LBB0_102
	v_lshl_add_u64 v[32:33], v[2:3], 2, s[6:7]
	s_waitcnt lgkmcnt(0)
	v_add_f32_e32 v29, v29, v30
	global_atomic_add_f32 v[32:33], v29, off offset:384

; __device__ __forceinline__ void filt_item(const Params& p, int lsel, int tile, float* lds, int wave, float (&colsum)[16], bool flush) {
;     ...
;         for (int ct = 0; ct < 16; ++ct) {
;             const int col = wv * 256 + ct * 16 + l15;
;             const float* wp = p.hy_pos_w3 + (size_t)g * 2048 + col;
;             f32x4 acc = (f32x4){0.f, 0.f, 0.f, 0.f};
; #pragma unroll
;             for (int s_ = 0; s_ < 16; ++s_) acc = __builtin_amdgcn_mfma_f32_16x16x4f32(av[s_], wp[(size_t)s_ * 4 * 2048], acc, 0, 0, 0);
;             const float dec = fabsf(p.hy_decay[col]); float asum = 0.f;
; #pragma unroll
;             for (int r = 0; r < 4; ++r) { const float tn = (float)(t0 + 4 * g + r) * inv_lm1; acc[r] *= __expf(-tn * dec); asum += fabsf(acc[r]); }
;             *(f32x4*)(filt + (size_t)col * L + t0 + 4 * g) = acc;
;             colsum[ct] += asum;
;             if (flush) { float tot = colsum[ct]; tot += __shfl_xor(tot, 16); tot += __shfl_xor(tot, 32); if (g == 0) atomicAdd(normsum + col, tot); colsum[ct] = 0.f; }
;         }
.LBB0_103:
	s_waitcnt lgkmcnt(0)
	v_add_co_u32_e32 v34, vcc, 0x38000, v6
	s_waitcnt vmcnt(8)
	v_mfma_f32_16x16x4_f32 v[30:33], v14, v216, 0
	v_addc_co_u32_e32 v35, vcc, 0, v7, vcc
	global_load_dword v29, v[34:35], off offset:448
	v_add_co_u32_e32 v34, vcc, 0x40000, v6
	s_nop 1
	v_addc_co_u32_e32 v35, vcc, 0, v7, vcc
	s_waitcnt vmcnt(8)
	v_mfma_f32_16x16x4_f32 v[30:33], v15, v217, v[30:33]
	global_load_dword v67, v[34:35], off offset:448
	v_add_co_u32_e32 v34, vcc, 0x48000, v6
	s_nop 1
	v_addc_co_u32_e32 v35, vcc, 0, v7, vcc
	s_waitcnt vmcnt(8)
	v_mfma_f32_16x16x4_f32 v[30:33], v18, v218, v[30:33]
	s_waitcnt vmcnt(7)
	v_mfma_f32_16x16x4_f32 v[30:33], v19, v219, v[30:33]
	global_load_dword v38, v[34:35], off offset:448
	v_add_co_u32_e32 v34, vcc, 0x50000, v6
	s_nop 1
	v_addc_co_u32_e32 v35, vcc, 0, v7, vcc
	s_waitcnt vmcnt(7)
	v_mfma_f32_16x16x4_f32 v[30:33], v8, v220, v[30:33]
	global_load_dword v39, v[34:35], off offset:448
	v_add_co_u32_e32 v34, vcc, 0x58000, v6
	s_nop 1
	v_addc_co_u32_e32 v35, vcc, 0, v7, vcc
	s_waitcnt vmcnt(7)
	v_mfma_f32_16x16x4_f32 v[30:33], v9, v221, v[30:33]
	global_load_dword v65, v[34:35], off offset:448
	v_add_co_u32_e32 v34, vcc, 0x60000, v6
	s_nop 1
	v_addc_co_u32_e32 v35, vcc, 0, v7, vcc
	s_waitcnt vmcnt(7)
	v_mfma_f32_16x16x4_f32 v[30:33], v10, v222, v[30:33]
	global_load_dword v66, v[34:35], off offset:448
	v_add_co_u32_e32 v34, vcc, 0x68000, v6
	s_nop 1
	v_addc_co_u32_e32 v35, vcc, 0, v7, vcc
	s_waitcnt vmcnt(5)
	v_mfma_f32_16x16x4_f32 v[30:33], v11, v29, v[30:33]
	global_load_dword v29, v[34:35], off offset:448
	v_add_co_u32_e32 v34, vcc, 0x70000, v6
	s_nop 1
	v_addc_co_u32_e32 v35, vcc, 0, v7, vcc
	v_add_co_u32_e32 v36, vcc, 0x78000, v6
	s_waitcnt vmcnt(5)
	v_mfma_f32_16x16x4_f32 v[30:33], v12, v67, v[30:33]
	v_addc_co_u32_e32 v37, vcc, 0, v7, vcc
	global_load_dword v67, v[34:35], off offset:448
	global_load_dword v68, v[36:37], off offset:448
	v_or_b32_e32 v34, 0x70, v2
	v_ashrrev_i32_e32 v35, 31, v34
	v_lshlrev_b64 v[34:35], s24, v[34:35]
	v_lshl_add_u64 v[34:35], v[34:35], 2, v[4:5]
	s_and_b64 vcc, exec, s[4:5]
	s_waitcnt vmcnt(6)
	v_mfma_f32_16x16x4_f32 v[30:33], v13, v38, v[30:33]
	s_waitcnt vmcnt(5)
	v_mfma_f32_16x16x4_f32 v[30:33], v20, v39, v[30:33]
	s_waitcnt vmcnt(4)
	v_mfma_f32_16x16x4_f32 v[30:33], v21, v65, v[30:33]
	s_waitcnt vmcnt(3)
	v_mfma_f32_16x16x4_f32 v[30:33], v24, v66, v[30:33]
	s_waitcnt vmcnt(2)
	v_mfma_f32_16x16x4_f32 v[30:33], v25, v29, v[30:33]
	global_load_dword v216, v[6:7], off offset:512
	global_load_dword v217, v[204:205], off offset:512
	global_load_dword v218, v[206:207], off offset:512
	global_load_dword v219, v[208:209], off offset:512
	global_load_dword v220, v[210:211], off offset:512
	global_load_dword v221, v[212:213], off offset:512
	global_load_dword v222, v[214:215], off offset:512
	global_load_dword v224, v[16:17], off offset:512
	v_mul_f32_e64 v36, v28, |v225|
	s_waitcnt vmcnt(9)
	v_mfma_f32_16x16x4_f32 v[30:33], v22, v67, v[30:33]
	v_mul_f32_e64 v37, v27, |v225|
	v_mul_f32_e64 v38, v26, |v225|
	v_mul_f32_e64 v29, v0, |v225|
	v_mul_f32_e32 v36, 0x3fb8aa3b, v36
	v_mul_f32_e32 v37, 0x3fb8aa3b, v37
	v_mul_f32_e32 v38, 0x3fb8aa3b, v38
	v_mul_f32_e32 v29, 0x3fb8aa3b, v29
	s_waitcnt vmcnt(8)
	v_mfma_f32_16x16x4_f32 v[30:33], v23, v68, v[30:33]
	v_exp_f32_e32 v36, v36
	v_exp_f32_e32 v37, v37
	v_exp_f32_e32 v38, v38
	v_exp_f32_e32 v39, v29
	s_nop 5
	v_pk_mul_f32 v[30:31], v[30:31], v[36:37]
	v_pk_mul_f32 v[32:33], v[32:33], v[38:39]
	v_add_f32_e64 v29, |v30|, |v31|
	v_add_f32_e64 v29, |v32|, v29
	v_add_f32_e64 v29, |v33|, v29
	v_add_f32_e32 v57, v57, v29
	global_store_dwordx4 v[34:35], v[30:33], off
	s_cbranch_vccnz .LBB0_107
	s_nop 0
	v_and_b32_e32 v30, 64, v48
	v_xor_b32_e32 v29, 16, v48
	v_add_u32_e32 v30, 64, v30
	v_cmp_lt_i32_e32 vcc, v29, v30
	v_xor_b32_e32 v31, 32, v48
	s_nop 0
	v_cndmask_b32_e32 v29, v48, v29, vcc
	v_lshlrev_b32_e32 v29, 2, v29
	ds_bpermute_b32 v29, v29, v57
	v_cmp_lt_i32_e32 vcc, v31, v30
	s_waitcnt lgkmcnt(0)
	v_add_f32_e32 v29, v57, v29
	v_cndmask_b32_e32 v30, v48, v31, vcc
	v_lshlrev_b32_e32 v30, 2, v30
	ds_bpermute_b32 v30, v30, v29
	s_and_saveexec_b64 s[8:9], s[0:1]
	s_cbranch_execz .LBB0_106
	v_lshl_add_u64 v[32:33], v[2:3], 2, s[6:7]
	s_waitcnt lgkmcnt(0)
	v_add_f32_e32 v29, v29, v30
	global_atomic_add_f32 v[32:33], v29, off offset:448

; __device__ __forceinline__ void filt_item(const Params& p, int lsel, int tile, float* lds, int wave, float (&colsum)[16], bool flush) {
;     ...
;         for (int ct = 0; ct < 16; ++ct) {
;             const int col = wv * 256 + ct * 16 + l15;
;             const float* wp = p.hy_pos_w3 + (size_t)g * 2048 + col;
;             f32x4 acc = (f32x4){0.f, 0.f, 0.f, 0.f};
; #pragma unroll
;             for (int s_ = 0; s_ < 16; ++s_) acc = __builtin_amdgcn_mfma_f32_16x16x4f32(av[s_], wp[(size_t)s_ * 4 * 2048], acc, 0, 0, 0);
;             const float dec = fabsf(p.hy_decay[col]); float asum = 0.f;
; #pragma unroll
;             for (int r = 0; r < 4; ++r) { const float tn = (float)(t0 + 4 * g + r) * inv_lm1; acc[r] *= __expf(-tn * dec); asum += fabsf(acc[r]); }
;             *(f32x4*)(filt + (size_t)col * L + t0 + 4 * g) = acc;
;             colsum[ct] += asum;
;             if (flush) { float tot = colsum[ct]; tot += __shfl_xor(tot, 16); tot += __shfl_xor(tot, 32); if (g == 0) atomicAdd(normsum + col, tot); colsum[ct] = 0.f; }
;         }
.LBB0_107:
	s_waitcnt lgkmcnt(0)
	v_add_co_u32_e32 v34, vcc, 0x38000, v6
	s_waitcnt vmcnt(8)
	v_mfma_f32_16x16x4_f32 v[30:33], v14, v216, 0
	v_addc_co_u32_e32 v35, vcc, 0, v7, vcc
	global_load_dword v29, v[34:35], off offset:512
	v_add_co_u32_e32 v34, vcc, 0x40000, v6
	s_nop 1
	v_addc_co_u32_e32 v35, vcc, 0, v7, vcc
	s_waitcnt vmcnt(8)
	v_mfma_f32_16x16x4_f32 v[30:33], v15, v217, v[30:33]
	global_load_dword v67, v[34:35], off offset:512
	v_add_co_u32_e32 v34, vcc, 0x48000, v6
	s_nop 1
	v_addc_co_u32_e32 v35, vcc, 0, v7, vcc
	s_waitcnt vmcnt(8)
	v_mfma_f32_16x16x4_f32 v[30:33], v18, v218, v[30:33]
	s_waitcnt vmcnt(7)
	v_mfma_f32_16x16x4_f32 v[30:33], v19, v219, v[30:33]
	global_load_dword v38, v[34:35], off offset:512
	v_add_co_u32_e32 v34, vcc, 0x50000, v6
	s_nop 1
	v_addc_co_u32_e32 v35, vcc, 0, v7, vcc
	s_waitcnt vmcnt(7)
	v_mfma_f32_16x16x4_f32 v[30:33], v8, v220, v[30:33]
	global_load_dword v39, v[34:35], off offset:512
	v_add_co_u32_e32 v34, vcc, 0x58000, v6
	s_nop 1
	v_addc_co_u32_e32 v35, vcc, 0, v7, vcc
	s_waitcnt vmcnt(7)
	v_mfma_f32_16x16x4_f32 v[30:33], v9, v221, v[30:33]
	global_load_dword v65, v[34:35], off offset:512
	v_add_co_u32_e32 v34, vcc, 0x60000, v6
	s_nop 1
	v_addc_co_u32_e32 v35, vcc, 0, v7, vcc
	s_waitcnt vmcnt(7)
	v_mfma_f32_16x16x4_f32 v[30:33], v10, v222, v[30:33]
	global_load_dword v66, v[34:35], off offset:512
	v_add_co_u32_e32 v34, vcc, 0x68000, v6
	s_nop 1
	v_addc_co_u32_e32 v35, vcc, 0, v7, vcc
	s_waitcnt vmcnt(5)
	v_mfma_f32_16x16x4_f32 v[30:33], v11, v29, v[30:33]
	global_load_dword v29, v[34:35], off offset:512
	v_add_co_u32_e32 v34, vcc, 0x70000, v6
	s_nop 1
	v_addc_co_u32_e32 v35, vcc, 0, v7, vcc
	v_add_co_u32_e32 v36, vcc, 0x78000, v6
	s_waitcnt vmcnt(5)
	v_mfma_f32_16x16x4_f32 v[30:33], v12, v67, v[30:33]
	v_addc_co_u32_e32 v37, vcc, 0, v7, vcc
	global_load_dword v67, v[34:35], off offset:512
	global_load_dword v68, v[36:37], off offset:512
	v_or_b32_e32 v34, 0x80, v2
	v_ashrrev_i32_e32 v35, 31, v34
	v_lshlrev_b64 v[34:35], s24, v[34:35]
	v_lshl_add_u64 v[34:35], v[34:35], 2, v[4:5]
	s_and_b64 vcc, exec, s[4:5]
	s_waitcnt vmcnt(6)
	v_mfma_f32_16x16x4_f32 v[30:33], v13, v38, v[30:33]
	s_waitcnt vmcnt(5)
	v_mfma_f32_16x16x4_f32 v[30:33], v20, v39, v[30:33]
	s_waitcnt vmcnt(4)
	v_mfma_f32_16x16x4_f32 v[30:33], v21, v65, v[30:33]
	s_waitcnt vmcnt(3)
	v_mfma_f32_16x16x4_f32 v[30:33], v24, v66, v[30:33]
	s_waitcnt vmcnt(2)
	v_mfma_f32_16x16x4_f32 v[30:33], v25, v29, v[30:33]
	global_load_dword v216, v[6:7], off offset:576
	global_load_dword v217, v[204:205], off offset:576
	global_load_dword v218, v[206:207], off offset:576
	global_load_dword v219, v[208:209], off offset:576
	global_load_dword v220, v[210:211], off offset:576
	global_load_dword v221, v[212:213], off offset:576
	global_load_dword v222, v[214:215], off offset:576
	global_load_dword v225, v[16:17], off offset:576
	v_mul_f32_e64 v36, v28, |v224|
	s_waitcnt vmcnt(9)
	v_mfma_f32_16x16x4_f32 v[30:33], v22, v67, v[30:33]
	v_mul_f32_e64 v37, v27, |v224|
	v_mul_f32_e64 v38, v26, |v224|
	v_mul_f32_e64 v29, v0, |v224|
	v_mul_f32_e32 v36, 0x3fb8aa3b, v36
	v_mul_f32_e32 v37, 0x3fb8aa3b, v37
	v_mul_f32_e32 v38, 0x3fb8aa3b, v38
	v_mul_f32_e32 v29, 0x3fb8aa3b, v29
	s_waitcnt vmcnt(8)
	v_mfma_f32_16x16x4_f32 v[30:33], v23, v68, v[30:33]
	v_exp_f32_e32 v36, v36
	v_exp_f32_e32 v37, v37
	v_exp_f32_e32 v38, v38
	v_exp_f32_e32 v39, v29
	s_nop 5
	v_pk_mul_f32 v[30:31], v[30:31], v[36:37]
	v_pk_mul_f32 v[32:33], v[32:33], v[38:39]
	v_add_f32_e64 v29, |v30|, |v31|
	v_add_f32_e64 v29, |v32|, v29
	v_add_f32_e64 v29, |v33|, v29
	v_add_f32_e32 v56, v56, v29
	global_store_dwordx4 v[34:35], v[30:33], off
	s_cbranch_vccnz .LBB0_111
	s_nop 0
	v_and_b32_e32 v30, 64, v48
	v_xor_b32_e32 v29, 16, v48
	v_add_u32_e32 v30, 64, v30
	v_cmp_lt_i32_e32 vcc, v29, v30
	v_xor_b32_e32 v31, 32, v48
	s_nop 0
	v_cndmask_b32_e32 v29, v48, v29, vcc
	v_lshlrev_b32_e32 v29, 2, v29
	ds_bpermute_b32 v29, v29, v56
	v_cmp_lt_i32_e32 vcc, v31, v30
	s_waitcnt lgkmcnt(0)
	v_add_f32_e32 v29, v56, v29
	v_cndmask_b32_e32 v30, v48, v31, vcc
	v_lshlrev_b32_e32 v30, 2, v30
	ds_bpermute_b32 v30, v30, v29
	s_and_saveexec_b64 s[8:9], s[0:1]
	s_cbranch_execz .LBB0_110
	v_lshl_add_u64 v[32:33], v[2:3], 2, s[6:7]
	s_waitcnt lgkmcnt(0)
	v_add_f32_e32 v29, v29, v30
	global_atomic_add_f32 v[32:33], v29, off offset:512

; __device__ __forceinline__ void filt_item(const Params& p, int lsel, int tile, float* lds, int wave, float (&colsum)[16], bool flush) {
;     ...
;         for (int ct = 0; ct < 16; ++ct) {
;             const int col = wv * 256 + ct * 16 + l15;
;             const float* wp = p.hy_pos_w3 + (size_t)g * 2048 + col;
;             f32x4 acc = (f32x4){0.f, 0.f, 0.f, 0.f};
; #pragma unroll
;             for (int s_ = 0; s_ < 16; ++s_) acc = __builtin_amdgcn_mfma_f32_16x16x4f32(av[s_], wp[(size_t)s_ * 4 * 2048], acc, 0, 0, 0);
;             const float dec = fabsf(p.hy_decay[col]); float asum = 0.f;
; #pragma unroll
;             for (int r = 0; r < 4; ++r) { const float tn = (float)(t0 + 4 * g + r) * inv_lm1; acc[r] *= __expf(-tn * dec); asum += fabsf(acc[r]); }
;             *(f32x4*)(filt + (size_t)col * L + t0 + 4 * g) = acc;
;             colsum[ct] += asum;
;             if (flush) { float tot = colsum[ct]; tot += __shfl_xor(tot, 16); tot += __shfl_xor(tot, 32); if (g == 0) atomicAdd(normsum + col, tot); colsum[ct] = 0.f; }
;         }
.LBB0_111:
	s_waitcnt lgkmcnt(0)
	v_add_co_u32_e32 v34, vcc, 0x38000, v6
	s_waitcnt vmcnt(8)
	v_mfma_f32_16x16x4_f32 v[30:33], v14, v216, 0
	v_addc_co_u32_e32 v35, vcc, 0, v7, vcc
	global_load_dword v29, v[34:35], off offset:576
	v_add_co_u32_e32 v34, vcc, 0x40000, v6
	s_nop 1
	v_addc_co_u32_e32 v35, vcc, 0, v7, vcc
	s_waitcnt vmcnt(8)
	v_mfma_f32_16x16x4_f32 v[30:33], v15, v217, v[30:33]
	global_load_dword v67, v[34:35], off offset:576
	v_add_co_u32_e32 v34, vcc, 0x48000, v6
	s_nop 1
	v_addc_co_u32_e32 v35, vcc, 0, v7, vcc
	s_waitcnt vmcnt(8)
	v_mfma_f32_16x16x4_f32 v[30:33], v18, v218, v[30:33]
	s_waitcnt vmcnt(7)
	v_mfma_f32_16x16x4_f32 v[30:33], v19, v219, v[30:33]
	global_load_dword v38, v[34:35], off offset:576
	v_add_co_u32_e32 v34, vcc, 0x50000, v6
	s_nop 1
	v_addc_co_u32_e32 v35, vcc, 0, v7, vcc
	s_waitcnt vmcnt(7)
	v_mfma_f32_16x16x4_f32 v[30:33], v8, v220, v[30:33]
	global_load_dword v39, v[34:35], off offset:576
	v_add_co_u32_e32 v34, vcc, 0x58000, v6
	s_nop 1
	v_addc_co_u32_e32 v35, vcc, 0, v7, vcc
	s_waitcnt vmcnt(7)
	v_mfma_f32_16x16x4_f32 v[30:33], v9, v221, v[30:33]
	global_load_dword v65, v[34:35], off offset:576
	v_add_co_u32_e32 v34, vcc, 0x60000, v6
	s_nop 1
	v_addc_co_u32_e32 v35, vcc, 0, v7, vcc
	s_waitcnt vmcnt(7)
	v_mfma_f32_16x16x4_f32 v[30:33], v10, v222, v[30:33]
	global_load_dword v66, v[34:35], off offset:576
	v_add_co_u32_e32 v34, vcc, 0x68000, v6
	s_nop 1
	v_addc_co_u32_e32 v35, vcc, 0, v7, vcc
	s_waitcnt vmcnt(5)
	v_mfma_f32_16x16x4_f32 v[30:33], v11, v29, v[30:33]
	global_load_dword v29, v[34:35], off offset:576
	v_add_co_u32_e32 v34, vcc, 0x70000, v6
	s_nop 1
	v_addc_co_u32_e32 v35, vcc, 0, v7, vcc
	v_add_co_u32_e32 v36, vcc, 0x78000, v6
	s_waitcnt vmcnt(5)
	v_mfma_f32_16x16x4_f32 v[30:33], v12, v67, v[30:33]
	v_addc_co_u32_e32 v37, vcc, 0, v7, vcc
	global_load_dword v67, v[34:35], off offset:576
	global_load_dword v68, v[36:37], off offset:576
	v_or_b32_e32 v34, 0x90, v2
	v_ashrrev_i32_e32 v35, 31, v34
	v_lshlrev_b64 v[34:35], s24, v[34:35]
	v_lshl_add_u64 v[34:35], v[34:35], 2, v[4:5]
	s_and_b64 vcc, exec, s[4:5]
	s_waitcnt vmcnt(6)
	v_mfma_f32_16x16x4_f32 v[30:33], v13, v38, v[30:33]
	s_waitcnt vmcnt(5)
	v_mfma_f32_16x16x4_f32 v[30:33], v20, v39, v[30:33]
	s_waitcnt vmcnt(4)
	v_mfma_f32_16x16x4_f32 v[30:33], v21, v65, v[30:33]
	s_waitcnt vmcnt(3)
	v_mfma_f32_16x16x4_f32 v[30:33], v24, v66, v[30:33]
	s_waitcnt vmcnt(2)
	v_mfma_f32_16x16x4_f32 v[30:33], v25, v29, v[30:33]
	global_load_dword v216, v[6:7], off offset:640
	global_load_dword v217, v[204:205], off offset:640
	global_load_dword v218, v[206:207], off offset:640
	global_load_dword v219, v[208:209], off offset:640
	global_load_dword v220, v[210:211], off offset:640
	global_load_dword v221, v[212:213], off offset:640
	global_load_dword v222, v[214:215], off offset:640
	global_load_dword v224, v[16:17], off offset:640
	v_mul_f32_e64 v36, v28, |v225|
	s_waitcnt vmcnt(9)
	v_mfma_f32_16x16x4_f32 v[30:33], v22, v67, v[30:33]
	v_mul_f32_e64 v37, v27, |v225|
	v_mul_f32_e64 v38, v26, |v225|
	v_mul_f32_e64 v29, v0, |v225|
	v_mul_f32_e32 v36, 0x3fb8aa3b, v36
	v_mul_f32_e32 v37, 0x3fb8aa3b, v37
	v_mul_f32_e32 v38, 0x3fb8aa3b, v38
	v_mul_f32_e32 v29, 0x3fb8aa3b, v29
	s_waitcnt vmcnt(8)
	v_mfma_f32_16x16x4_f32 v[30:33], v23, v68, v[30:33]
	v_exp_f32_e32 v36, v36
	v_exp_f32_e32 v37, v37
	v_exp_f32_e32 v38, v38
	v_exp_f32_e32 v39, v29
	s_nop 5
	v_pk_mul_f32 v[30:31], v[30:31], v[36:37]
	v_pk_mul_f32 v[32:33], v[32:33], v[38:39]
	v_add_f32_e64 v29, |v30|, |v31|
	v_add_f32_e64 v29, |v32|, v29
	v_add_f32_e64 v29, |v33|, v29
	v_add_f32_e32 v55, v55, v29
	global_store_dwordx4 v[34:35], v[30:33], off
	s_cbranch_vccnz .LBB0_115
	s_nop 0
	v_and_b32_e32 v30, 64, v48
	v_xor_b32_e32 v29, 16, v48
	v_add_u32_e32 v30, 64, v30
	v_cmp_lt_i32_e32 vcc, v29, v30
	v_xor_b32_e32 v31, 32, v48
	s_nop 0
	v_cndmask_b32_e32 v29, v48, v29, vcc
	v_lshlrev_b32_e32 v29, 2, v29
	ds_bpermute_b32 v29, v29, v55
	v_cmp_lt_i32_e32 vcc, v31, v30
	s_waitcnt lgkmcnt(0)
	v_add_f32_e32 v29, v55, v29
	v_cndmask_b32_e32 v30, v48, v31, vcc
	v_lshlrev_b32_e32 v30, 2, v30
	ds_bpermute_b32 v30, v30, v29
	s_and_saveexec_b64 s[8:9], s[0:1]
	s_cbranch_execz .LBB0_114
	v_lshl_add_u64 v[32:33], v[2:3], 2, s[6:7]
	s_waitcnt lgkmcnt(0)
	v_add_f32_e32 v29, v29, v30
	global_atomic_add_f32 v[32:33], v29, off offset:576

; __device__ __forceinline__ void filt_item(const Params& p, int lsel, int tile, float* lds, int wave, float (&colsum)[16], bool flush) {
;     ...
;         for (int ct = 0; ct < 16; ++ct) {
;             const int col = wv * 256 + ct * 16 + l15;
;             const float* wp = p.hy_pos_w3 + (size_t)g * 2048 + col;
;             f32x4 acc = (f32x4){0.f, 0.f, 0.f, 0.f};
; #pragma unroll
;             for (int s_ = 0; s_ < 16; ++s_) acc = __builtin_amdgcn_mfma_f32_16x16x4f32(av[s_], wp[(size_t)s_ * 4 * 2048], acc, 0, 0, 0);
;             const float dec = fabsf(p.hy_decay[col]); float asum = 0.f;
; #pragma unroll
;             for (int r = 0; r < 4; ++r) { const float tn = (float)(t0 + 4 * g + r) * inv_lm1; acc[r] *= __expf(-tn * dec); asum += fabsf(acc[r]); }
;             *(f32x4*)(filt + (size_t)col * L + t0 + 4 * g) = acc;
;             colsum[ct] += asum;
;             if (flush) { float tot = colsum[ct]; tot += __shfl_xor(tot, 16); tot += __shfl_xor(tot, 32); if (g == 0) atomicAdd(normsum + col, tot); colsum[ct] = 0.f; }
;         }
.LBB0_115:
	s_waitcnt lgkmcnt(0)
	v_add_co_u32_e32 v34, vcc, 0x38000, v6
	s_waitcnt vmcnt(8)
	v_mfma_f32_16x16x4_f32 v[30:33], v14, v216, 0
	v_addc_co_u32_e32 v35, vcc, 0, v7, vcc
	global_load_dword v29, v[34:35], off offset:640
	v_add_co_u32_e32 v34, vcc, 0x40000, v6
	s_nop 1
	v_addc_co_u32_e32 v35, vcc, 0, v7, vcc
	s_waitcnt vmcnt(8)
	v_mfma_f32_16x16x4_f32 v[30:33], v15, v217, v[30:33]
	global_load_dword v67, v[34:35], off offset:640
	v_add_co_u32_e32 v34, vcc, 0x48000, v6
	s_nop 1
	v_addc_co_u32_e32 v35, vcc, 0, v7, vcc
	s_waitcnt vmcnt(8)
	v_mfma_f32_16x16x4_f32 v[30:33], v18, v218, v[30:33]
	s_waitcnt vmcnt(7)
	v_mfma_f32_16x16x4_f32 v[30:33], v19, v219, v[30:33]
	global_load_dword v38, v[34:35], off offset:640
	v_add_co_u32_e32 v34, vcc, 0x50000, v6
	s_nop 1
	v_addc_co_u32_e32 v35, vcc, 0, v7, vcc
	s_waitcnt vmcnt(7)
	v_mfma_f32_16x16x4_f32 v[30:33], v8, v220, v[30:33]
	global_load_dword v39, v[34:35], off offset:640
	v_add_co_u32_e32 v34, vcc, 0x58000, v6
	s_nop 1
	v_addc_co_u32_e32 v35, vcc, 0, v7, vcc
	s_waitcnt vmcnt(7)
	v_mfma_f32_16x16x4_f32 v[30:33], v9, v221, v[30:33]
	global_load_dword v65, v[34:35], off offset:640
	v_add_co_u32_e32 v34, vcc, 0x60000, v6
	s_nop 1
	v_addc_co_u32_e32 v35, vcc, 0, v7, vcc
	s_waitcnt vmcnt(7)
	v_mfma_f32_16x16x4_f32 v[30:33], v10, v222, v[30:33]
	global_load_dword v66, v[34:35], off offset:640
	v_add_co_u32_e32 v34, vcc, 0x68000, v6
	s_nop 1
	v_addc_co_u32_e32 v35, vcc, 0, v7, vcc
	s_waitcnt vmcnt(5)
	v_mfma_f32_16x16x4_f32 v[30:33], v11, v29, v[30:33]
	global_load_dword v29, v[34:35], off offset:640
	v_add_co_u32_e32 v34, vcc, 0x70000, v6
	s_nop 1
	v_addc_co_u32_e32 v35, vcc, 0, v7, vcc
	v_add_co_u32_e32 v36, vcc, 0x78000, v6
	s_waitcnt vmcnt(5)
	v_mfma_f32_16x16x4_f32 v[30:33], v12, v67, v[30:33]
	v_addc_co_u32_e32 v37, vcc, 0, v7, vcc
	global_load_dword v67, v[34:35], off offset:640
	global_load_dword v68, v[36:37], off offset:640
	v_or_b32_e32 v34, 0xa0, v2
	v_ashrrev_i32_e32 v35, 31, v34
	v_lshlrev_b64 v[34:35], s24, v[34:35]
	v_lshl_add_u64 v[34:35], v[34:35], 2, v[4:5]
	s_and_b64 vcc, exec, s[4:5]
	s_waitcnt vmcnt(6)
	v_mfma_f32_16x16x4_f32 v[30:33], v13, v38, v[30:33]
	s_waitcnt vmcnt(5)
	v_mfma_f32_16x16x4_f32 v[30:33], v20, v39, v[30:33]
	s_waitcnt vmcnt(4)
	v_mfma_f32_16x16x4_f32 v[30:33], v21, v65, v[30:33]
	s_waitcnt vmcnt(3)
	v_mfma_f32_16x16x4_f32 v[30:33], v24, v66, v[30:33]
	s_waitcnt vmcnt(2)
	v_mfma_f32_16x16x4_f32 v[30:33], v25, v29, v[30:33]
	global_load_dword v216, v[6:7], off offset:704
	global_load_dword v217, v[204:205], off offset:704
	global_load_dword v218, v[206:207], off offset:704
	global_load_dword v219, v[208:209], off offset:704
	global_load_dword v220, v[210:211], off offset:704
	global_load_dword v221, v[212:213], off offset:704
	global_load_dword v222, v[214:215], off offset:704
	global_load_dword v225, v[16:17], off offset:704
	v_mul_f32_e64 v36, v28, |v224|
	s_waitcnt vmcnt(9)
	v_mfma_f32_16x16x4_f32 v[30:33], v22, v67, v[30:33]
	v_mul_f32_e64 v37, v27, |v224|
	v_mul_f32_e64 v38, v26, |v224|
	v_mul_f32_e64 v29, v0, |v224|
	v_mul_f32_e32 v36, 0x3fb8aa3b, v36
	v_mul_f32_e32 v37, 0x3fb8aa3b, v37
	v_mul_f32_e32 v38, 0x3fb8aa3b, v38
	v_mul_f32_e32 v29, 0x3fb8aa3b, v29
	s_waitcnt vmcnt(8)
	v_mfma_f32_16x16x4_f32 v[30:33], v23, v68, v[30:33]
	v_exp_f32_e32 v36, v36
	v_exp_f32_e32 v37, v37
	v_exp_f32_e32 v38, v38
	v_exp_f32_e32 v39, v29
	s_nop 5
	v_pk_mul_f32 v[30:31], v[30:31], v[36:37]
	v_pk_mul_f32 v[32:33], v[32:33], v[38:39]
	v_add_f32_e64 v29, |v30|, |v31|
	v_add_f32_e64 v29, |v32|, v29
	v_add_f32_e64 v29, |v33|, v29
	v_add_f32_e32 v54, v54, v29
	global_store_dwordx4 v[34:35], v[30:33], off
	s_cbranch_vccnz .LBB0_119
	s_nop 0
	v_and_b32_e32 v30, 64, v48
	v_xor_b32_e32 v29, 16, v48
	v_add_u32_e32 v30, 64, v30
	v_cmp_lt_i32_e32 vcc, v29, v30
	v_xor_b32_e32 v31, 32, v48
	s_nop 0
	v_cndmask_b32_e32 v29, v48, v29, vcc
	v_lshlrev_b32_e32 v29, 2, v29
	ds_bpermute_b32 v29, v29, v54
	v_cmp_lt_i32_e32 vcc, v31, v30
	s_waitcnt lgkmcnt(0)
	v_add_f32_e32 v29, v54, v29
	v_cndmask_b32_e32 v30, v48, v31, vcc
	v_lshlrev_b32_e32 v30, 2, v30
	ds_bpermute_b32 v30, v30, v29
	s_and_saveexec_b64 s[8:9], s[0:1]
	s_cbranch_execz .LBB0_118
	v_lshl_add_u64 v[32:33], v[2:3], 2, s[6:7]
	s_waitcnt lgkmcnt(0)
	v_add_f32_e32 v29, v29, v30
	global_atomic_add_f32 v[32:33], v29, off offset:640

; __device__ __forceinline__ void filt_item(const Params& p, int lsel, int tile, float* lds, int wave, float (&colsum)[16], bool flush) {
;     ...
;         for (int ct = 0; ct < 16; ++ct) {
;             const int col = wv * 256 + ct * 16 + l15;
;             const float* wp = p.hy_pos_w3 + (size_t)g * 2048 + col;
;             f32x4 acc = (f32x4){0.f, 0.f, 0.f, 0.f};
; #pragma unroll
;             for (int s_ = 0; s_ < 16; ++s_) acc = __builtin_amdgcn_mfma_f32_16x16x4f32(av[s_], wp[(size_t)s_ * 4 * 2048], acc, 0, 0, 0);
;             const float dec = fabsf(p.hy_decay[col]); float asum = 0.f;
; #pragma unroll
;             for (int r = 0; r < 4; ++r) { const float tn = (float)(t0 + 4 * g + r) * inv_lm1; acc[r] *= __expf(-tn * dec); asum += fabsf(acc[r]); }
;             *(f32x4*)(filt + (size_t)col * L + t0 + 4 * g) = acc;
;             colsum[ct] += asum;
;             if (flush) { float tot = colsum[ct]; tot += __shfl_xor(tot, 16); tot += __shfl_xor(tot, 32); if (g == 0) atomicAdd(normsum + col, tot); colsum[ct] = 0.f; }
;         }
.LBB0_119:
	s_waitcnt lgkmcnt(0)
	v_add_co_u32_e32 v34, vcc, 0x38000, v6
	s_waitcnt vmcnt(8)
	v_mfma_f32_16x16x4_f32 v[30:33], v14, v216, 0
	v_addc_co_u32_e32 v35, vcc, 0, v7, vcc
	global_load_dword v29, v[34:35], off offset:704
	v_add_co_u32_e32 v34, vcc, 0x40000, v6
	s_nop 1
	v_addc_co_u32_e32 v35, vcc, 0, v7, vcc
	s_waitcnt vmcnt(8)
	v_mfma_f32_16x16x4_f32 v[30:33], v15, v217, v[30:33]
	global_load_dword v67, v[34:35], off offset:704
	v_add_co_u32_e32 v34, vcc, 0x48000, v6
	s_nop 1
	v_addc_co_u32_e32 v35, vcc, 0, v7, vcc
	s_waitcnt vmcnt(8)
	v_mfma_f32_16x16x4_f32 v[30:33], v18, v218, v[30:33]
	s_waitcnt vmcnt(7)
	v_mfma_f32_16x16x4_f32 v[30:33], v19, v219, v[30:33]
	global_load_dword v38, v[34:35], off offset:704
	v_add_co_u32_e32 v34, vcc, 0x50000, v6
	s_nop 1
	v_addc_co_u32_e32 v35, vcc, 0, v7, vcc
	s_waitcnt vmcnt(7)
	v_mfma_f32_16x16x4_f32 v[30:33], v8, v220, v[30:33]
	global_load_dword v39, v[34:35], off offset:704
	v_add_co_u32_e32 v34, vcc, 0x58000, v6
	s_nop 1
	v_addc_co_u32_e32 v35, vcc, 0, v7, vcc
	s_waitcnt vmcnt(7)
	v_mfma_f32_16x16x4_f32 v[30:33], v9, v221, v[30:33]
	global_load_dword v65, v[34:35], off offset:704
	v_add_co_u32_e32 v34, vcc, 0x60000, v6
	s_nop 1
	v_addc_co_u32_e32 v35, vcc, 0, v7, vcc
	s_waitcnt vmcnt(7)
	v_mfma_f32_16x16x4_f32 v[30:33], v10, v222, v[30:33]
	global_load_dword v66, v[34:35], off offset:704
	v_add_co_u32_e32 v34, vcc, 0x68000, v6
	s_nop 1
	v_addc_co_u32_e32 v35, vcc, 0, v7, vcc
	s_waitcnt vmcnt(5)
	v_mfma_f32_16x16x4_f32 v[30:33], v11, v29, v[30:33]
	global_load_dword v29, v[34:35], off offset:704
	v_add_co_u32_e32 v34, vcc, 0x70000, v6
	s_nop 1
	v_addc_co_u32_e32 v35, vcc, 0, v7, vcc
	v_add_co_u32_e32 v36, vcc, 0x78000, v6
	s_waitcnt vmcnt(5)
	v_mfma_f32_16x16x4_f32 v[30:33], v12, v67, v[30:33]
	v_addc_co_u32_e32 v37, vcc, 0, v7, vcc
	global_load_dword v67, v[34:35], off offset:704
	global_load_dword v68, v[36:37], off offset:704
	v_or_b32_e32 v34, 0xb0, v2
	v_ashrrev_i32_e32 v35, 31, v34
	v_lshlrev_b64 v[34:35], s24, v[34:35]
	v_lshl_add_u64 v[34:35], v[34:35], 2, v[4:5]
	s_and_b64 vcc, exec, s[4:5]
	s_waitcnt vmcnt(6)
	v_mfma_f32_16x16x4_f32 v[30:33], v13, v38, v[30:33]
	s_waitcnt vmcnt(5)
	v_mfma_f32_16x16x4_f32 v[30:33], v20, v39, v[30:33]
	s_waitcnt vmcnt(4)
	v_mfma_f32_16x16x4_f32 v[30:33], v21, v65, v[30:33]
	s_waitcnt vmcnt(3)
	v_mfma_f32_16x16x4_f32 v[30:33], v24, v66, v[30:33]
	s_waitcnt vmcnt(2)
	v_mfma_f32_16x16x4_f32 v[30:33], v25, v29, v[30:33]
	global_load_dword v216, v[6:7], off offset:768
	global_load_dword v217, v[204:205], off offset:768
	global_load_dword v218, v[206:207], off offset:768
	global_load_dword v219, v[208:209], off offset:768
	global_load_dword v220, v[210:211], off offset:768
	global_load_dword v221, v[212:213], off offset:768
	global_load_dword v222, v[214:215], off offset:768
	global_load_dword v224, v[16:17], off offset:768
	v_mul_f32_e64 v36, v28, |v225|
	s_waitcnt vmcnt(9)
	v_mfma_f32_16x16x4_f32 v[30:33], v22, v67, v[30:33]
	v_mul_f32_e64 v37, v27, |v225|
	v_mul_f32_e64 v38, v26, |v225|
	v_mul_f32_e64 v29, v0, |v225|
	v_mul_f32_e32 v36, 0x3fb8aa3b, v36
	v_mul_f32_e32 v37, 0x3fb8aa3b, v37
	v_mul_f32_e32 v38, 0x3fb8aa3b, v38
	v_mul_f32_e32 v29, 0x3fb8aa3b, v29
	s_waitcnt vmcnt(8)
	v_mfma_f32_16x16x4_f32 v[30:33], v23, v68, v[30:33]
	v_exp_f32_e32 v36, v36
	v_exp_f32_e32 v37, v37
	v_exp_f32_e32 v38, v38
	v_exp_f32_e32 v39, v29
	s_nop 5
	v_pk_mul_f32 v[30:31], v[30:31], v[36:37]
	v_pk_mul_f32 v[32:33], v[32:33], v[38:39]
	v_add_f32_e64 v29, |v30|, |v31|
	v_add_f32_e64 v29, |v32|, v29
	v_add_f32_e64 v29, |v33|, v29
	v_add_f32_e32 v53, v53, v29
	global_store_dwordx4 v[34:35], v[30:33], off
	s_cbranch_vccnz .LBB0_123
	s_nop 0
	v_and_b32_e32 v30, 64, v48
	v_xor_b32_e32 v29, 16, v48
	v_add_u32_e32 v30, 64, v30
	v_cmp_lt_i32_e32 vcc, v29, v30
	v_xor_b32_e32 v31, 32, v48
	s_nop 0
	v_cndmask_b32_e32 v29, v48, v29, vcc
	v_lshlrev_b32_e32 v29, 2, v29
	ds_bpermute_b32 v29, v29, v53
	v_cmp_lt_i32_e32 vcc, v31, v30
	s_waitcnt lgkmcnt(0)
	v_add_f32_e32 v29, v53, v29
	v_cndmask_b32_e32 v30, v48, v31, vcc
	v_lshlrev_b32_e32 v30, 2, v30
	ds_bpermute_b32 v30, v30, v29
	s_and_saveexec_b64 s[8:9], s[0:1]
	s_cbranch_execz .LBB0_122
	v_lshl_add_u64 v[32:33], v[2:3], 2, s[6:7]
	s_waitcnt lgkmcnt(0)
	v_add_f32_e32 v29, v29, v30
	global_atomic_add_f32 v[32:33], v29, off offset:704

; __device__ __forceinline__ void filt_item(const Params& p, int lsel, int tile, float* lds, int wave, float (&colsum)[16], bool flush) {
;     ...
;         for (int ct = 0; ct < 16; ++ct) {
;             const int col = wv * 256 + ct * 16 + l15;
;             const float* wp = p.hy_pos_w3 + (size_t)g * 2048 + col;
;             f32x4 acc = (f32x4){0.f, 0.f, 0.f, 0.f};
; #pragma unroll
;             for (int s_ = 0; s_ < 16; ++s_) acc = __builtin_amdgcn_mfma_f32_16x16x4f32(av[s_], wp[(size_t)s_ * 4 * 2048], acc, 0, 0, 0);
;             const float dec = fabsf(p.hy_decay[col]); float asum = 0.f;
; #pragma unroll
;             for (int r = 0; r < 4; ++r) { const float tn = (float)(t0 + 4 * g + r) * inv_lm1; acc[r] *= __expf(-tn * dec); asum += fabsf(acc[r]); }
;             *(f32x4*)(filt + (size_t)col * L + t0 + 4 * g) = acc;
;             colsum[ct] += asum;
;             if (flush) { float tot = colsum[ct]; tot += __shfl_xor(tot, 16); tot += __shfl_xor(tot, 32); if (g == 0) atomicAdd(normsum + col, tot); colsum[ct] = 0.f; }
;         }
.LBB0_123:
	s_waitcnt lgkmcnt(0)
	v_add_co_u32_e32 v34, vcc, 0x38000, v6
	s_waitcnt vmcnt(8)
	v_mfma_f32_16x16x4_f32 v[30:33], v14, v216, 0
	v_addc_co_u32_e32 v35, vcc, 0, v7, vcc
	global_load_dword v29, v[34:35], off offset:768
	v_add_co_u32_e32 v34, vcc, 0x40000, v6
	s_nop 1
	v_addc_co_u32_e32 v35, vcc, 0, v7, vcc
	s_waitcnt vmcnt(8)
	v_mfma_f32_16x16x4_f32 v[30:33], v15, v217, v[30:33]
	global_load_dword v67, v[34:35], off offset:768
	v_add_co_u32_e32 v34, vcc, 0x48000, v6
	s_nop 1
	v_addc_co_u32_e32 v35, vcc, 0, v7, vcc
	s_waitcnt vmcnt(8)
	v_mfma_f32_16x16x4_f32 v[30:33], v18, v218, v[30:33]
	s_waitcnt vmcnt(7)
	v_mfma_f32_16x16x4_f32 v[30:33], v19, v219, v[30:33]
	global_load_dword v38, v[34:35], off offset:768
	v_add_co_u32_e32 v34, vcc, 0x50000, v6
	s_nop 1
	v_addc_co_u32_e32 v35, vcc, 0, v7, vcc
	s_waitcnt vmcnt(7)
	v_mfma_f32_16x16x4_f32 v[30:33], v8, v220, v[30:33]
	global_load_dword v39, v[34:35], off offset:768
	v_add_co_u32_e32 v34, vcc, 0x58000, v6
	s_nop 1
	v_addc_co_u32_e32 v35, vcc, 0, v7, vcc
	s_waitcnt vmcnt(7)
	v_mfma_f32_16x16x4_f32 v[30:33], v9, v221, v[30:33]
	global_load_dword v65, v[34:35], off offset:768
	v_add_co_u32_e32 v34, vcc, 0x60000, v6
	s_nop 1
	v_addc_co_u32_e32 v35, vcc, 0, v7, vcc
	s_waitcnt vmcnt(7)
	v_mfma_f32_16x16x4_f32 v[30:33], v10, v222, v[30:33]
	global_load_dword v66, v[34:35], off offset:768
	v_add_co_u32_e32 v34, vcc, 0x68000, v6
	s_nop 1
	v_addc_co_u32_e32 v35, vcc, 0, v7, vcc
	s_waitcnt vmcnt(5)
	v_mfma_f32_16x16x4_f32 v[30:33], v11, v29, v[30:33]
	global_load_dword v29, v[34:35], off offset:768
	v_add_co_u32_e32 v34, vcc, 0x70000, v6
	s_nop 1
	v_addc_co_u32_e32 v35, vcc, 0, v7, vcc
	v_add_co_u32_e32 v36, vcc, 0x78000, v6
	s_waitcnt vmcnt(5)
	v_mfma_f32_16x16x4_f32 v[30:33], v12, v67, v[30:33]
	v_addc_co_u32_e32 v37, vcc, 0, v7, vcc
	global_load_dword v67, v[34:35], off offset:768
	global_load_dword v68, v[36:37], off offset:768
	v_or_b32_e32 v34, 0xc0, v2
	v_ashrrev_i32_e32 v35, 31, v34
	v_lshlrev_b64 v[34:35], s24, v[34:35]
	v_lshl_add_u64 v[34:35], v[34:35], 2, v[4:5]
	s_and_b64 vcc, exec, s[4:5]
	s_waitcnt vmcnt(6)
	v_mfma_f32_16x16x4_f32 v[30:33], v13, v38, v[30:33]
	s_waitcnt vmcnt(5)
	v_mfma_f32_16x16x4_f32 v[30:33], v20, v39, v[30:33]
	s_waitcnt vmcnt(4)
	v_mfma_f32_16x16x4_f32 v[30:33], v21, v65, v[30:33]
	s_waitcnt vmcnt(3)
	v_mfma_f32_16x16x4_f32 v[30:33], v24, v66, v[30:33]
	s_waitcnt vmcnt(2)
	v_mfma_f32_16x16x4_f32 v[30:33], v25, v29, v[30:33]
	global_load_dword v216, v[6:7], off offset:832
	global_load_dword v217, v[204:205], off offset:832
	global_load_dword v218, v[206:207], off offset:832
	global_load_dword v219, v[208:209], off offset:832
	global_load_dword v220, v[210:211], off offset:832
	global_load_dword v221, v[212:213], off offset:832
	global_load_dword v222, v[214:215], off offset:832
	global_load_dword v225, v[16:17], off offset:832
	v_mul_f32_e64 v36, v28, |v224|
	s_waitcnt vmcnt(9)
	v_mfma_f32_16x16x4_f32 v[30:33], v22, v67, v[30:33]
	v_mul_f32_e64 v37, v27, |v224|
	v_mul_f32_e64 v38, v26, |v224|
	v_mul_f32_e64 v29, v0, |v224|
	v_mul_f32_e32 v36, 0x3fb8aa3b, v36
	v_mul_f32_e32 v37, 0x3fb8aa3b, v37
	v_mul_f32_e32 v38, 0x3fb8aa3b, v38
	v_mul_f32_e32 v29, 0x3fb8aa3b, v29
	s_waitcnt vmcnt(8)
	v_mfma_f32_16x16x4_f32 v[30:33], v23, v68, v[30:33]
	v_exp_f32_e32 v36, v36
	v_exp_f32_e32 v37, v37
	v_exp_f32_e32 v38, v38
	v_exp_f32_e32 v39, v29
	s_nop 5
	v_pk_mul_f32 v[30:31], v[30:31], v[36:37]
	v_pk_mul_f32 v[32:33], v[32:33], v[38:39]
	v_add_f32_e64 v29, |v30|, |v31|
	v_add_f32_e64 v29, |v32|, v29
	v_add_f32_e64 v29, |v33|, v29
	v_add_f32_e32 v52, v52, v29
	global_store_dwordx4 v[34:35], v[30:33], off
	s_cbranch_vccnz .LBB0_127
	s_nop 0
	v_and_b32_e32 v30, 64, v48
	v_xor_b32_e32 v29, 16, v48
	v_add_u32_e32 v30, 64, v30
	v_cmp_lt_i32_e32 vcc, v29, v30
	v_xor_b32_e32 v31, 32, v48
	s_nop 0
	v_cndmask_b32_e32 v29, v48, v29, vcc
	v_lshlrev_b32_e32 v29, 2, v29
	ds_bpermute_b32 v29, v29, v52
	v_cmp_lt_i32_e32 vcc, v31, v30
	s_waitcnt lgkmcnt(0)
	v_add_f32_e32 v29, v52, v29
	v_cndmask_b32_e32 v30, v48, v31, vcc
	v_lshlrev_b32_e32 v30, 2, v30
	ds_bpermute_b32 v30, v30, v29
	s_and_saveexec_b64 s[8:9], s[0:1]
	s_cbranch_execz .LBB0_126
	v_lshl_add_u64 v[32:33], v[2:3], 2, s[6:7]
	s_waitcnt lgkmcnt(0)
	v_add_f32_e32 v29, v29, v30
	global_atomic_add_f32 v[32:33], v29, off offset:768

; __device__ __forceinline__ void filt_item(const Params& p, int lsel, int tile, float* lds, int wave, float (&colsum)[16], bool flush) {
;     ...
;         for (int ct = 0; ct < 16; ++ct) {
;             const int col = wv * 256 + ct * 16 + l15;
;             const float* wp = p.hy_pos_w3 + (size_t)g * 2048 + col;
;             f32x4 acc = (f32x4){0.f, 0.f, 0.f, 0.f};
; #pragma unroll
;             for (int s_ = 0; s_ < 16; ++s_) acc = __builtin_amdgcn_mfma_f32_16x16x4f32(av[s_], wp[(size_t)s_ * 4 * 2048], acc, 0, 0, 0);
;             const float dec = fabsf(p.hy_decay[col]); float asum = 0.f;
; #pragma unroll
;             for (int r = 0; r < 4; ++r) { const float tn = (float)(t0 + 4 * g + r) * inv_lm1; acc[r] *= __expf(-tn * dec); asum += fabsf(acc[r]); }
;             *(f32x4*)(filt + (size_t)col * L + t0 + 4 * g) = acc;
;             colsum[ct] += asum;
;             if (flush) { float tot = colsum[ct]; tot += __shfl_xor(tot, 16); tot += __shfl_xor(tot, 32); if (g == 0) atomicAdd(normsum + col, tot); colsum[ct] = 0.f; }
;         }
.LBB0_127:
	s_waitcnt lgkmcnt(0)
	v_add_co_u32_e32 v34, vcc, 0x38000, v6
	s_waitcnt vmcnt(8)
	v_mfma_f32_16x16x4_f32 v[30:33], v14, v216, 0
	v_addc_co_u32_e32 v35, vcc, 0, v7, vcc
	global_load_dword v29, v[34:35], off offset:832
	v_add_co_u32_e32 v34, vcc, 0x40000, v6
	s_nop 1
	v_addc_co_u32_e32 v35, vcc, 0, v7, vcc
	s_waitcnt vmcnt(8)
	v_mfma_f32_16x16x4_f32 v[30:33], v15, v217, v[30:33]
	global_load_dword v67, v[34:35], off offset:832
	v_add_co_u32_e32 v34, vcc, 0x48000, v6
	s_nop 1
	v_addc_co_u32_e32 v35, vcc, 0, v7, vcc
	s_waitcnt vmcnt(8)
	v_mfma_f32_16x16x4_f32 v[30:33], v18, v218, v[30:33]
	s_waitcnt vmcnt(7)
	v_mfma_f32_16x16x4_f32 v[30:33], v19, v219, v[30:33]
	global_load_dword v38, v[34:35], off offset:832
	v_add_co_u32_e32 v34, vcc, 0x50000, v6
	s_nop 1
	v_addc_co_u32_e32 v35, vcc, 0, v7, vcc
	s_waitcnt vmcnt(7)
	v_mfma_f32_16x16x4_f32 v[30:33], v8, v220, v[30:33]
	global_load_dword v39, v[34:35], off offset:832
	v_add_co_u32_e32 v34, vcc, 0x58000, v6
	s_nop 1
	v_addc_co_u32_e32 v35, vcc, 0, v7, vcc
	s_waitcnt vmcnt(7)
	v_mfma_f32_16x16x4_f32 v[30:33], v9, v221, v[30:33]
	global_load_dword v65, v[34:35], off offset:832
	v_add_co_u32_e32 v34, vcc, 0x60000, v6
	s_nop 1
	v_addc_co_u32_e32 v35, vcc, 0, v7, vcc
	s_waitcnt vmcnt(7)
	v_mfma_f32_16x16x4_f32 v[30:33], v10, v222, v[30:33]
	global_load_dword v66, v[34:35], off offset:832
	v_add_co_u32_e32 v34, vcc, 0x68000, v6
	s_nop 1
	v_addc_co_u32_e32 v35, vcc, 0, v7, vcc
	s_waitcnt vmcnt(5)
	v_mfma_f32_16x16x4_f32 v[30:33], v11, v29, v[30:33]
	global_load_dword v29, v[34:35], off offset:832
	v_add_co_u32_e32 v34, vcc, 0x70000, v6
	s_nop 1
	v_addc_co_u32_e32 v35, vcc, 0, v7, vcc
	v_add_co_u32_e32 v36, vcc, 0x78000, v6
	s_waitcnt vmcnt(5)
	v_mfma_f32_16x16x4_f32 v[30:33], v12, v67, v[30:33]
	v_addc_co_u32_e32 v37, vcc, 0, v7, vcc
	global_load_dword v67, v[34:35], off offset:832
	global_load_dword v68, v[36:37], off offset:832
	v_or_b32_e32 v34, 0xd0, v2
	v_ashrrev_i32_e32 v35, 31, v34
	v_lshlrev_b64 v[34:35], s24, v[34:35]
	v_lshl_add_u64 v[34:35], v[34:35], 2, v[4:5]
	s_and_b64 vcc, exec, s[4:5]
	s_waitcnt vmcnt(6)
	v_mfma_f32_16x16x4_f32 v[30:33], v13, v38, v[30:33]
	s_waitcnt vmcnt(5)
	v_mfma_f32_16x16x4_f32 v[30:33], v20, v39, v[30:33]
	s_waitcnt vmcnt(4)
	v_mfma_f32_16x16x4_f32 v[30:33], v21, v65, v[30:33]
	s_waitcnt vmcnt(3)
	v_mfma_f32_16x16x4_f32 v[30:33], v24, v66, v[30:33]
	s_waitcnt vmcnt(2)
	v_mfma_f32_16x16x4_f32 v[30:33], v25, v29, v[30:33]
	global_load_dword v216, v[6:7], off offset:896
	global_load_dword v217, v[204:205], off offset:896
	global_load_dword v218, v[206:207], off offset:896
	global_load_dword v219, v[208:209], off offset:896
	global_load_dword v220, v[210:211], off offset:896
	global_load_dword v221, v[212:213], off offset:896
	global_load_dword v222, v[214:215], off offset:896
	global_load_dword v224, v[16:17], off offset:896
	v_mul_f32_e64 v36, v28, |v225|
	s_waitcnt vmcnt(9)
	v_mfma_f32_16x16x4_f32 v[30:33], v22, v67, v[30:33]
	v_mul_f32_e64 v37, v27, |v225|
	v_mul_f32_e64 v38, v26, |v225|
	v_mul_f32_e64 v29, v0, |v225|
	v_mul_f32_e32 v36, 0x3fb8aa3b, v36
	v_mul_f32_e32 v37, 0x3fb8aa3b, v37
	v_mul_f32_e32 v38, 0x3fb8aa3b, v38
	v_mul_f32_e32 v29, 0x3fb8aa3b, v29
	s_waitcnt vmcnt(8)
	v_mfma_f32_16x16x4_f32 v[30:33], v23, v68, v[30:33]
	v_exp_f32_e32 v36, v36
	v_exp_f32_e32 v37, v37
	v_exp_f32_e32 v38, v38
	v_exp_f32_e32 v39, v29
	s_nop 5
	v_pk_mul_f32 v[30:31], v[30:31], v[36:37]
	v_pk_mul_f32 v[32:33], v[32:33], v[38:39]
	v_add_f32_e64 v29, |v30|, |v31|
	v_add_f32_e64 v29, |v32|, v29
	v_add_f32_e64 v29, |v33|, v29
	v_add_f32_e32 v51, v51, v29
	global_store_dwordx4 v[34:35], v[30:33], off
	s_cbranch_vccnz .LBB0_131
	s_nop 0
	v_and_b32_e32 v30, 64, v48
	v_xor_b32_e32 v29, 16, v48
	v_add_u32_e32 v30, 64, v30
	v_cmp_lt_i32_e32 vcc, v29, v30
	v_xor_b32_e32 v31, 32, v48
	s_nop 0
	v_cndmask_b32_e32 v29, v48, v29, vcc
	v_lshlrev_b32_e32 v29, 2, v29
	ds_bpermute_b32 v29, v29, v51
	v_cmp_lt_i32_e32 vcc, v31, v30
	s_waitcnt lgkmcnt(0)
	v_add_f32_e32 v29, v51, v29
	v_cndmask_b32_e32 v30, v48, v31, vcc
	v_lshlrev_b32_e32 v30, 2, v30
	ds_bpermute_b32 v30, v30, v29
	s_and_saveexec_b64 s[8:9], s[0:1]
	s_cbranch_execz .LBB0_130
	v_lshl_add_u64 v[32:33], v[2:3], 2, s[6:7]
	s_waitcnt lgkmcnt(0)
	v_add_f32_e32 v29, v29, v30
	global_atomic_add_f32 v[32:33], v29, off offset:832

; __device__ __forceinline__ void filt_item(const Params& p, int lsel, int tile, float* lds, int wave, float (&colsum)[16], bool flush) {
;     ...
;         for (int ct = 0; ct < 16; ++ct) {
;             const int col = wv * 256 + ct * 16 + l15;
;             const float* wp = p.hy_pos_w3 + (size_t)g * 2048 + col;
;             f32x4 acc = (f32x4){0.f, 0.f, 0.f, 0.f};
; #pragma unroll
;             for (int s_ = 0; s_ < 16; ++s_) acc = __builtin_amdgcn_mfma_f32_16x16x4f32(av[s_], wp[(size_t)s_ * 4 * 2048], acc, 0, 0, 0);
;             const float dec = fabsf(p.hy_decay[col]); float asum = 0.f;
; #pragma unroll
;             for (int r = 0; r < 4; ++r) { const float tn = (float)(t0 + 4 * g + r) * inv_lm1; acc[r] *= __expf(-tn * dec); asum += fabsf(acc[r]); }
;             *(f32x4*)(filt + (size_t)col * L + t0 + 4 * g) = acc;
;             colsum[ct] += asum;
;             if (flush) { float tot = colsum[ct]; tot += __shfl_xor(tot, 16); tot += __shfl_xor(tot, 32); if (g == 0) atomicAdd(normsum + col, tot); colsum[ct] = 0.f; }
;         }
.LBB0_131:
	s_waitcnt lgkmcnt(0)
	v_add_co_u32_e32 v34, vcc, 0x38000, v6
	s_waitcnt vmcnt(8)
	v_mfma_f32_16x16x4_f32 v[30:33], v14, v216, 0
	v_addc_co_u32_e32 v35, vcc, 0, v7, vcc
	global_load_dword v29, v[34:35], off offset:896
	v_add_co_u32_e32 v34, vcc, 0x40000, v6
	s_nop 1
	v_addc_co_u32_e32 v35, vcc, 0, v7, vcc
	s_waitcnt vmcnt(8)
	v_mfma_f32_16x16x4_f32 v[30:33], v15, v217, v[30:33]
	global_load_dword v67, v[34:35], off offset:896
	v_add_co_u32_e32 v34, vcc, 0x48000, v6
	s_nop 1
	v_addc_co_u32_e32 v35, vcc, 0, v7, vcc
	s_waitcnt vmcnt(8)
	v_mfma_f32_16x16x4_f32 v[30:33], v18, v218, v[30:33]
	s_waitcnt vmcnt(7)
	v_mfma_f32_16x16x4_f32 v[30:33], v19, v219, v[30:33]
	global_load_dword v38, v[34:35], off offset:896
	v_add_co_u32_e32 v34, vcc, 0x50000, v6
	s_nop 1
	v_addc_co_u32_e32 v35, vcc, 0, v7, vcc
	s_waitcnt vmcnt(7)
	v_mfma_f32_16x16x4_f32 v[30:33], v8, v220, v[30:33]
	global_load_dword v39, v[34:35], off offset:896
	v_add_co_u32_e32 v34, vcc, 0x58000, v6
	s_nop 1
	v_addc_co_u32_e32 v35, vcc, 0, v7, vcc
	s_waitcnt vmcnt(7)
	v_mfma_f32_16x16x4_f32 v[30:33], v9, v221, v[30:33]
	global_load_dword v65, v[34:35], off offset:896
	v_add_co_u32_e32 v34, vcc, 0x60000, v6
	s_nop 1
	v_addc_co_u32_e32 v35, vcc, 0, v7, vcc
	s_waitcnt vmcnt(7)
	v_mfma_f32_16x16x4_f32 v[30:33], v10, v222, v[30:33]
	global_load_dword v66, v[34:35], off offset:896
	v_add_co_u32_e32 v34, vcc, 0x68000, v6
	s_nop 1
	v_addc_co_u32_e32 v35, vcc, 0, v7, vcc
	s_waitcnt vmcnt(5)
	v_mfma_f32_16x16x4_f32 v[30:33], v11, v29, v[30:33]
	global_load_dword v29, v[34:35], off offset:896
	v_add_co_u32_e32 v34, vcc, 0x70000, v6
	s_nop 1
	v_addc_co_u32_e32 v35, vcc, 0, v7, vcc
	v_add_co_u32_e32 v36, vcc, 0x78000, v6
	s_waitcnt vmcnt(5)
	v_mfma_f32_16x16x4_f32 v[30:33], v12, v67, v[30:33]
	v_addc_co_u32_e32 v37, vcc, 0, v7, vcc
	global_load_dword v67, v[34:35], off offset:896
	global_load_dword v68, v[36:37], off offset:896
	v_or_b32_e32 v34, 0xe0, v2
	v_ashrrev_i32_e32 v35, 31, v34
	v_lshlrev_b64 v[34:35], s24, v[34:35]
	v_lshl_add_u64 v[34:35], v[34:35], 2, v[4:5]
	s_and_b64 vcc, exec, s[4:5]
	s_waitcnt vmcnt(6)
	v_mfma_f32_16x16x4_f32 v[30:33], v13, v38, v[30:33]
	s_waitcnt vmcnt(5)
	v_mfma_f32_16x16x4_f32 v[30:33], v20, v39, v[30:33]
	s_waitcnt vmcnt(4)
	v_mfma_f32_16x16x4_f32 v[30:33], v21, v65, v[30:33]
	s_waitcnt vmcnt(3)
	v_mfma_f32_16x16x4_f32 v[30:33], v24, v66, v[30:33]
	s_waitcnt vmcnt(2)
	v_mfma_f32_16x16x4_f32 v[30:33], v25, v29, v[30:33]
	global_load_dword v216, v[6:7], off offset:960
	global_load_dword v217, v[204:205], off offset:960
	global_load_dword v218, v[206:207], off offset:960
	global_load_dword v219, v[208:209], off offset:960
	global_load_dword v220, v[210:211], off offset:960
	global_load_dword v221, v[212:213], off offset:960
	global_load_dword v222, v[214:215], off offset:960
	global_load_dword v225, v[16:17], off offset:960
	v_mul_f32_e64 v36, v28, |v224|
	s_waitcnt vmcnt(9)
	v_mfma_f32_16x16x4_f32 v[30:33], v22, v67, v[30:33]
	v_mul_f32_e64 v37, v27, |v224|
	v_mul_f32_e64 v38, v26, |v224|
	v_mul_f32_e64 v29, v0, |v224|
	v_mul_f32_e32 v36, 0x3fb8aa3b, v36
	v_mul_f32_e32 v37, 0x3fb8aa3b, v37
	v_mul_f32_e32 v38, 0x3fb8aa3b, v38
	v_mul_f32_e32 v29, 0x3fb8aa3b, v29
	s_waitcnt vmcnt(8)
	v_mfma_f32_16x16x4_f32 v[30:33], v23, v68, v[30:33]
	v_exp_f32_e32 v36, v36
	v_exp_f32_e32 v37, v37
	v_exp_f32_e32 v38, v38
	v_exp_f32_e32 v39, v29
	s_nop 5
	v_pk_mul_f32 v[30:31], v[30:31], v[36:37]
	v_pk_mul_f32 v[32:33], v[32:33], v[38:39]
	v_add_f32_e64 v29, |v30|, |v31|
	v_add_f32_e64 v29, |v32|, v29
	v_add_f32_e64 v29, |v33|, v29
	v_add_f32_e32 v50, v50, v29
	global_store_dwordx4 v[34:35], v[30:33], off
	s_cbranch_vccnz .LBB0_135
	s_nop 0
	v_and_b32_e32 v30, 64, v48
	v_xor_b32_e32 v29, 16, v48
	v_add_u32_e32 v30, 64, v30
	v_cmp_lt_i32_e32 vcc, v29, v30
	v_xor_b32_e32 v31, 32, v48
	s_nop 0
	v_cndmask_b32_e32 v29, v48, v29, vcc
	v_lshlrev_b32_e32 v29, 2, v29
	ds_bpermute_b32 v29, v29, v50
	v_cmp_lt_i32_e32 vcc, v31, v30
	s_waitcnt lgkmcnt(0)
	v_add_f32_e32 v29, v50, v29
	v_cndmask_b32_e32 v30, v48, v31, vcc
	v_lshlrev_b32_e32 v30, 2, v30
	ds_bpermute_b32 v30, v30, v29
	s_and_saveexec_b64 s[8:9], s[0:1]
	s_cbranch_execz .LBB0_134
	v_lshl_add_u64 v[32:33], v[2:3], 2, s[6:7]
	s_waitcnt lgkmcnt(0)
	v_add_f32_e32 v29, v29, v30
	global_atomic_add_f32 v[32:33], v29, off offset:896

; __device__ __forceinline__ void filt_item(const Params& p, int lsel, int tile, float* lds, int wave, float (&colsum)[16], bool flush) {
;     ...
;         for (int ct = 0; ct < 16; ++ct) {
;             const int col = wv * 256 + ct * 16 + l15;
;             const float* wp = p.hy_pos_w3 + (size_t)g * 2048 + col;
;             f32x4 acc = (f32x4){0.f, 0.f, 0.f, 0.f};
; #pragma unroll
;             for (int s_ = 0; s_ < 16; ++s_) acc = __builtin_amdgcn_mfma_f32_16x16x4f32(av[s_], wp[(size_t)s_ * 4 * 2048], acc, 0, 0, 0);
;             const float dec = fabsf(p.hy_decay[col]); float asum = 0.f;
; #pragma unroll
;             for (int r = 0; r < 4; ++r) { const float tn = (float)(t0 + 4 * g + r) * inv_lm1; acc[r] *= __expf(-tn * dec); asum += fabsf(acc[r]); }
;             *(f32x4*)(filt + (size_t)col * L + t0 + 4 * g) = acc;
;             colsum[ct] += asum;
;             if (flush) { float tot = colsum[ct]; tot += __shfl_xor(tot, 16); tot += __shfl_xor(tot, 32); if (g == 0) atomicAdd(normsum + col, tot); colsum[ct] = 0.f; }
;         }
.LBB0_135:
	s_waitcnt lgkmcnt(0)
	v_add_co_u32_e32 v34, vcc, 0x38000, v6
	s_waitcnt vmcnt(8)
	v_mfma_f32_16x16x4_f32 v[30:33], v14, v216, 0
	v_addc_co_u32_e32 v35, vcc, 0, v7, vcc
	global_load_dword v29, v[34:35], off offset:960
	v_add_co_u32_e32 v34, vcc, 0x40000, v6
	s_nop 1
	v_addc_co_u32_e32 v35, vcc, 0, v7, vcc
	global_load_dword v34, v[34:35], off offset:960
	s_waitcnt vmcnt(9)
	v_mfma_f32_16x16x4_f32 v[30:33], v15, v217, v[30:33]
	v_add_co_u32_e32 v14, vcc, 0x48000, v6
	s_nop 1
	v_addc_co_u32_e32 v15, vcc, 0, v7, vcc
	s_waitcnt vmcnt(8)
	v_mfma_f32_16x16x4_f32 v[30:33], v18, v218, v[30:33]
	global_load_dword v18, v[14:15], off offset:960
	v_add_co_u32_e32 v14, vcc, 0x50000, v6
	s_nop 1
	v_addc_co_u32_e32 v15, vcc, 0, v7, vcc
	s_waitcnt vmcnt(8)
	v_mfma_f32_16x16x4_f32 v[30:33], v19, v219, v[30:33]
	global_load_dword v19, v[14:15], off offset:960
	v_add_co_u32_e32 v14, vcc, 0x58000, v6
	s_nop 1
	v_addc_co_u32_e32 v15, vcc, 0, v7, vcc
	global_load_dword v35, v[14:15], off offset:960
	s_waitcnt vmcnt(9)
	v_mfma_f32_16x16x4_f32 v[30:33], v8, v220, v[30:33]
	v_add_co_u32_e32 v8, vcc, 0x60000, v6
	s_waitcnt vmcnt(8)
	v_mfma_f32_16x16x4_f32 v[30:33], v9, v221, v[30:33]
	v_addc_co_u32_e32 v9, vcc, 0, v7, vcc
	global_load_dword v36, v[8:9], off offset:960
	v_add_co_u32_e32 v14, vcc, 0x68000, v6
	s_nop 1
	v_addc_co_u32_e32 v15, vcc, 0, v7, vcc
	s_waitcnt vmcnt(8)
	v_mfma_f32_16x16x4_f32 v[30:33], v10, v222, v[30:33]
	s_waitcnt vmcnt(5)
	v_mfma_f32_16x16x4_f32 v[8:11], v11, v29, v[30:33]
	global_load_dword v29, v[14:15], off offset:960
	v_add_co_u32_e32 v14, vcc, 0x70000, v6
	s_nop 1
	v_addc_co_u32_e32 v15, vcc, 0, v7, vcc
	v_add_co_u32_e32 v6, vcc, 0x78000, v6
	s_waitcnt vmcnt(5)
	v_mfma_f32_16x16x4_f32 v[8:11], v12, v34, v[8:11]
	v_addc_co_u32_e32 v7, vcc, 0, v7, vcc
	global_load_dword v12, v[14:15], off offset:960
	s_nop 0
	global_load_dword v14, v[6:7], off offset:960
	s_and_b64 vcc, exec, s[4:5]
	s_waitcnt vmcnt(6)
	v_mfma_f32_16x16x4_f32 v[6:9], v13, v18, v[8:11]
	s_nop 1
	v_or_b32_e32 v10, 0xf0, v2
	v_ashrrev_i32_e32 v11, 31, v10
	v_lshlrev_b64 v[10:11], s24, v[10:11]
	v_lshl_add_u64 v[10:11], v[10:11], 2, v[4:5]
	v_mul_f32_e64 v15, v28, |v225|
	s_waitcnt vmcnt(5)
	v_mfma_f32_16x16x4_f32 v[6:9], v20, v19, v[6:9]
	v_mul_f32_e64 v16, v27, |v225|
	v_mul_f32_e64 v17, v26, |v225|
	v_mul_f32_e64 v0, v0, |v225|
	v_mul_f32_e32 v13, 0x3fb8aa3b, v16
	v_mul_f32_e32 v0, 0x3fb8aa3b, v0
	v_exp_f32_e32 v13, v13
	s_waitcnt vmcnt(4)
	v_mfma_f32_16x16x4_f32 v[6:9], v21, v35, v[6:9]
	s_waitcnt vmcnt(3)
	v_mfma_f32_16x16x4_f32 v[6:9], v24, v36, v[6:9]
	s_waitcnt vmcnt(2)
	v_mfma_f32_16x16x4_f32 v[6:9], v25, v29, v[6:9]
	s_waitcnt vmcnt(1)
	v_mfma_f32_16x16x4_f32 v[6:9], v22, v12, v[6:9]
	v_mul_f32_e32 v12, 0x3fb8aa3b, v15
	v_mul_f32_e32 v15, 0x3fb8aa3b, v17
	v_exp_f32_e32 v12, v12
	s_waitcnt vmcnt(0)
	v_mfma_f32_16x16x4_f32 v[6:9], v23, v14, v[6:9]
	v_exp_f32_e32 v14, v15
	v_exp_f32_e32 v15, v0
	s_nop 7
	v_pk_mul_f32 v[4:5], v[6:7], v[12:13]
	v_pk_mul_f32 v[6:7], v[8:9], v[14:15]
	v_add_f32_e64 v0, |v4|, |v5|
	v_add_f32_e64 v0, |v6|, v0
	v_add_f32_e64 v0, |v7|, v0
	v_add_f32_e32 v49, v49, v0
	global_store_dwordx4 v[10:11], v[4:7], off
	s_cbranch_vccnz .LBB0_16
	s_nop 0
	v_and_b32_e32 v4, 64, v48
	v_xor_b32_e32 v0, 16, v48
	v_add_u32_e32 v4, 64, v4
	v_cmp_lt_i32_e32 vcc, v0, v4
	v_xor_b32_e32 v5, 32, v48
	s_nop 0
	v_cndmask_b32_e32 v0, v48, v0, vcc
	v_lshlrev_b32_e32 v0, 2, v0
	ds_bpermute_b32 v0, v0, v49
	v_cmp_lt_i32_e32 vcc, v5, v4
	s_waitcnt lgkmcnt(0)
	v_add_f32_e32 v0, v49, v0
	v_cndmask_b32_e32 v4, v48, v5, vcc
	v_lshlrev_b32_e32 v4, 2, v4
	ds_bpermute_b32 v4, v4, v0
	s_and_saveexec_b64 s[4:5], s[0:1]
	s_cbranch_execz .LBB0_15
	v_lshl_add_u64 v[2:3], v[2:3], 2, s[6:7]
	s_waitcnt lgkmcnt(0)
	v_add_f32_e32 v0, v0, v4
	global_atomic_add_f32 v[2:3], v0, off offset:960
	s_branch .LBB0_15
